# v_m4 + scan loop: staging-load addresses advanced incrementally by a scalar-selected stride (3 VALU + SALU per chunk instead of 27 VALU)
# speedup vs baseline: 1.0085x; 1.0080x over previous
; DI void scan_item(const Params& p, int item, char* smem) {
;     ...
;   auto gload = [&](int ci) {
; #pragma unroll
;     for (int i = 0; i < 3; i++) {
;       int id = tid + i * 256;
;       int st = id / 48, rem = id % 48, vec = rem >> 3, part = rem & 7;
;       int t = tof(ci * 16 + st);
;       int vi = vec < 3 ? vec : vec + 3 * dir;
;       rg_[i] = *(const u32x4*)(SIb + ((long)t * 9 + vi) * 64 + part * 8);
;     }
;   };
;     ...
;   auto ldstep = [&](const float* b) {
;     StepIn x;
;     x.r = *(const f32x4v*)(b + cg4); x.k = *(const f32x4v*)(b + 64 + cg4); x.v = b[voff];
;     x.w = *(const f32x4v*)(b + 192 + cg4); x.d = *(const f32x4v*)(b + 256 + cg4); x.b = *(const f32x4v*)(b + 320 + cg4);
;     return x;
;   };
;   for (int ci = 0; ci < nch; ci++) {
;     if (ci + 1 < nch) gload(ci + 1);
;     const float* base = sIn + (ci & 1) * 16 * 6 * 64;
;     float ykeep = 0.f;
;     StepIn cur = ldstep(base);
; #pragma unroll
;     for (int st = 0; st < 16; st++) {
;       StepIn nxt = cur;
;       if (st + 1 < 16) nxt = ldstep(base + (st + 1) * 6 * 64);
;       __builtin_amdgcn_sched_barrier(0);
;       f32x2 ra = {cur.r.x, cur.r.y}, rb = {cur.r.z, cur.r.w}, ka = {cur.k.x, cur.k.y}, kb = {cur.k.z, cur.k.w};
;       f32x2 wa = {cur.w.x, cur.w.y}, wb = {cur.w.z, cur.w.w}, da = {cur.d.x, cur.d.y}, db = {cur.d.z, cur.d.w};
;       f32x2 ba = {cur.b.x, cur.b.y}, bb2 = {cur.b.z, cur.b.w};
;       f32x2 pp = Sa * ka + Sb * kb;
;       float sa = allreduce16(pp.x + pp.y);
;       f32x2 vv2 = {cur.v, cur.v};
;       f32x2 sa2 = {sa, sa};
;       Sa = (Sa * wa + vv2 * da) - sa2 * ba;
;       Sb = (Sb * wb + vv2 * db) - sa2 * bb2;
;       f32x2 yy = Sa * ra + Sb * rb;
;       float y = allreduce16(yy.x + yy.y);
;       ykeep = (l16 == st) ? y : ykeep;
;       cur = nxt;
;     }
.LBB0_398:
	v_lshlrev_b32_e32 v49, 2, v37
	v_lshlrev_b32_e32 v50, 2, v41
	v_mad_u32_u24 v32, v13, 6, v12
	v_mad_u32_u24 v33, v17, 6, v16
	v_mad_u32_u24 v34, v21, 6, v20
	v_lshl_or_b32 v32, v32, 8, v38
	v_lshl_or_b32 v33, v33, 8, v39
	v_lshl_or_b32 v34, v34, 8, v40
	s_movk_i32 s72, 0x10
	v_add_u32_e32 v0, s72, v13
	v_add_u32_e32 v4, s72, v17
	v_add_u32_e32 v8, s72, v21
	v_cmp_lt_i32_e32 vcc, 0xff, v0
	s_nop 1
	v_cndmask_b32_e32 v1, v208, v209, vcc
	v_cmp_lt_i32_e32 vcc, 0xff, v4
	v_sub_u32_e32 v1, v1, v0
	v_cndmask_b32_e64 v0, v1, v0, s[36:37]
	v_cndmask_b32_e32 v5, v208, v209, vcc
	v_cmp_lt_i32_e32 vcc, 0xff, v8
	v_sub_u32_e32 v5, v5, v4
	v_cndmask_b32_e64 v4, v5, v4, s[36:37]
	v_cndmask_b32_e32 v9, v208, v209, vcc
	v_sub_u32_e32 v9, v9, v8
	v_cndmask_b32_e64 v8, v9, v8, s[36:37]
	v_mad_i64_i32 v[0:1], s[12:13], v0, 9, v[14:15]
	v_mad_i64_i32 v[4:5], s[12:13], v4, 9, v[18:19]
	v_mad_i64_i32 v[8:9], s[12:13], v8, 9, v[22:23]
	v_lshlrev_b64 v[0:1], 7, v[0:1]
	v_lshlrev_b64 v[4:5], 7, v[4:5]
	v_lshlrev_b64 v[8:9], 7, v[8:9]
	v_lshl_add_u64 v[0:1], v[24:25], 0, v[0:1]
	v_lshl_add_u64 v[4:5], v[26:27], 0, v[4:5]
	v_lshl_add_u64 v[8:9], v[28:29], 0, v[8:9]
	v_mov_b64_e32 v[236:237], v[0:1]
	v_mov_b64_e32 v[238:239], v[4:5]
	v_mov_b64_e32 v[240:241], v[8:9]
	global_load_dwordx4 v[0:3], v[236:237], off
	global_load_dwordx4 v[4:7], v[238:239], off
	global_load_dwordx4 v[8:11], v[240:241], off
	s_mov_b32 s26, 0
.Lscan_loop:
	ds_read_b128 v[72:75], v49 offset:256
	ds_read_b32 v88, v50 offset:512
	ds_read_b128 v[80:83], v49 offset:1024
	ds_read_b128 v[76:79], v49 offset:768
	ds_read_b128 v[84:87], v49 offset:1280
	ds_read_b128 v[68:71], v49
	ds_read_b128 v[100:103], v49 offset:1792
	ds_read_b32 v116, v50 offset:2048
	ds_read_b128 v[108:111], v49 offset:2560
	ds_read_b128 v[104:107], v49 offset:2304
	ds_read_b128 v[112:115], v49 offset:2816
	ds_read_b128 v[96:99], v49 offset:1536
	s_add_i32 s72, s26, 32
	s_mov_b32 vcc_hi, 0x4c3800
	s_cmp_eq_u32 s72, 0x100
	s_cselect_b32 vcc_lo, vcc_hi, 0xffffb800
	s_cmp_lg_u32 s36, 0
	s_cselect_b32 vcc_lo, 0x4800, vcc_lo
	s_cmp_ge_u32 s72, 0x1100
	s_cselect_b32 vcc_lo, 0, vcc_lo
	s_ashr_i32 vcc_hi, vcc_lo, 31
	v_lshl_add_u64 v[236:237], v[236:237], 0, vcc
	v_lshl_add_u64 v[238:239], v[238:239], 0, vcc
	v_lshl_add_u64 v[240:241], v[240:241], 0, vcc
	global_load_dwordx4 v[162:165], v[236:237], off
	global_load_dwordx4 v[166:169], v[238:239], off
	global_load_dwordx4 v[170:173], v[240:241], off
	s_waitcnt lgkmcnt(6)
	ds_read_b128 v[122:125], v49 offset:3328
	ds_read_b32 v138, v50 offset:3584
	ds_read_b128 v[130:133], v49 offset:4096
	ds_read_b128 v[126:129], v49 offset:3840
	ds_read_b128 v[134:137], v49 offset:4352
	ds_read_b128 v[118:121], v49 offset:3072
	v_pk_mul_f32 v[56:57], v[90:91], v[72:73]
	v_pk_mul_f32 v[60:61], v[88:89], v[80:81] op_sel_hi:[0,1]
	v_pk_fma_f32 v[56:57], v[92:93], v[74:75], v[56:57]
	v_pk_mul_f32 v[62:63], v[88:89], v[82:83] op_sel_hi:[0,1]
	v_add_f32_e32 v58, v56, v57
	v_pk_fma_f32 v[60:61], v[90:91], v[76:77], v[60:61]
	v_pk_fma_f32 v[62:63], v[92:93], v[78:79], v[62:63]
	v_add_f32_dpp v58, v58, v58 quad_perm:[1,0,3,2] row_mask:0xf bank_mask:0xf bound_ctrl:1
	s_nop 1
	v_add_f32_dpp v58, v58, v58 quad_perm:[2,3,0,1] row_mask:0xf bank_mask:0xf bound_ctrl:1
	s_nop 1
	v_add_f32_dpp v58, v58, v58 row_half_mirror row_mask:0xf bank_mask:0xf bound_ctrl:1
	s_nop 1
	v_add_f32_dpp v58, v58, v58 row_mirror row_mask:0xf bank_mask:0xf bound_ctrl:1
	s_nop 0
	v_pk_fma_f32 v[90:91], v[84:85], v[58:59], v[60:61] op_sel_hi:[1,0,1] neg_lo:[1,0,0] neg_hi:[1,0,0]
	v_pk_fma_f32 v[92:93], v[86:87], v[58:59], v[62:63] op_sel_hi:[1,0,1] neg_lo:[1,0,0] neg_hi:[1,0,0]
	s_waitcnt lgkmcnt(6)
	ds_read_b128 v[144:147], v49 offset:4864
	ds_read_b32 v160, v50 offset:5120
	ds_read_b128 v[152:155], v49 offset:5632
	ds_read_b128 v[148:151], v49 offset:5376
	ds_read_b128 v[156:159], v49 offset:5888
	ds_read_b128 v[140:143], v49 offset:4608
	v_pk_mul_f32 v[56:57], v[90:91], v[100:101]
	v_pk_mul_f32 v[64:65], v[70:71], v[92:93]
	v_pk_fma_f32 v[56:57], v[92:93], v[102:103], v[56:57]
	v_pk_fma_f32 v[64:65], v[68:69], v[90:91], v[64:65]
	v_add_f32_e32 v58, v56, v57
	v_add_f32_e32 v66, v64, v65
	v_pk_mul_f32 v[60:61], v[116:117], v[108:109] op_sel_hi:[0,1]
	v_add_f32_dpp v58, v58, v58 quad_perm:[1,0,3,2] row_mask:0xf bank_mask:0xf bound_ctrl:1
	v_add_f32_dpp v66, v66, v66 quad_perm:[1,0,3,2] row_mask:0xf bank_mask:0xf bound_ctrl:1
	v_pk_fma_f32 v[60:61], v[90:91], v[104:105], v[60:61]
	v_add_f32_dpp v58, v58, v58 quad_perm:[2,3,0,1] row_mask:0xf bank_mask:0xf bound_ctrl:1
	v_add_f32_dpp v66, v66, v66 quad_perm:[2,3,0,1] row_mask:0xf bank_mask:0xf bound_ctrl:1
	v_pk_mul_f32 v[62:63], v[116:117], v[110:111] op_sel_hi:[0,1]
	v_add_f32_dpp v58, v58, v58 row_half_mirror row_mask:0xf bank_mask:0xf bound_ctrl:1
	v_add_f32_dpp v66, v66, v66 row_half_mirror row_mask:0xf bank_mask:0xf bound_ctrl:1
	v_pk_fma_f32 v[62:63], v[92:93], v[106:107], v[62:63]
	v_add_f32_dpp v58, v58, v58 row_mirror row_mask:0xf bank_mask:0xf bound_ctrl:1
	v_add_f32_dpp v66, v66, v66 row_mirror row_mask:0xf bank_mask:0xf bound_ctrl:1
	v_pk_fma_f32 v[90:91], v[112:113], v[58:59], v[60:61] op_sel_hi:[1,0,1] neg_lo:[1,0,0] neg_hi:[1,0,0]
	v_pk_fma_f32 v[92:93], v[114:115], v[58:59], v[62:63] op_sel_hi:[1,0,1] neg_lo:[1,0,0] neg_hi:[1,0,0]
	v_cndmask_b32_e64 v67, 0, v66, s[38:39]
	s_waitcnt lgkmcnt(6)
; DI void scan_item(const Params& p, int item, char* smem) {
;     ...
;     for (int st = 0; st < 16; st++) {
;       StepIn nxt = cur;
;       if (st + 1 < 16) nxt = ldstep(base + (st + 1) * 6 * 64);
;       __builtin_amdgcn_sched_barrier(0);
;       f32x2 ra = {cur.r.x, cur.r.y}, rb = {cur.r.z, cur.r.w}, ka = {cur.k.x, cur.k.y}, kb = {cur.k.z, cur.k.w};
;       f32x2 wa = {cur.w.x, cur.w.y}, wb = {cur.w.z, cur.w.w}, da = {cur.d.x, cur.d.y}, db = {cur.d.z, cur.d.w};
;       f32x2 ba = {cur.b.x, cur.b.y}, bb2 = {cur.b.z, cur.b.w};
;       f32x2 pp = Sa * ka + Sb * kb;
;       float sa = allreduce16(pp.x + pp.y);
;       f32x2 vv2 = {cur.v, cur.v};
;       f32x2 sa2 = {sa, sa};
;       Sa = (Sa * wa + vv2 * da) - sa2 * ba;
;       Sb = (Sb * wb + vv2 * db) - sa2 * bb2;
;       f32x2 yy = Sa * ra + Sb * rb;
;       float y = allreduce16(yy.x + yy.y);
;       ykeep = (l16 == st) ? y : ykeep;
;       cur = nxt;
;     }
	ds_read_b128 v[72:75], v49 offset:6400
	ds_read_b32 v88, v50 offset:6656
	ds_read_b128 v[80:83], v49 offset:7168
	ds_read_b128 v[76:79], v49 offset:6912
	ds_read_b128 v[84:87], v49 offset:7424
	ds_read_b128 v[68:71], v49 offset:6144
	v_pk_mul_f32 v[56:57], v[90:91], v[122:123]
	v_pk_mul_f32 v[64:65], v[98:99], v[92:93]
	v_pk_fma_f32 v[56:57], v[92:93], v[124:125], v[56:57]
	v_pk_fma_f32 v[64:65], v[96:97], v[90:91], v[64:65]
	v_add_f32_e32 v58, v56, v57
	v_add_f32_e32 v66, v64, v65
	v_pk_mul_f32 v[60:61], v[138:139], v[130:131] op_sel_hi:[0,1]
	v_add_f32_dpp v58, v58, v58 quad_perm:[1,0,3,2] row_mask:0xf bank_mask:0xf bound_ctrl:1
	v_add_f32_dpp v66, v66, v66 quad_perm:[1,0,3,2] row_mask:0xf bank_mask:0xf bound_ctrl:1
	v_pk_fma_f32 v[60:61], v[90:91], v[126:127], v[60:61]
	v_add_f32_dpp v58, v58, v58 quad_perm:[2,3,0,1] row_mask:0xf bank_mask:0xf bound_ctrl:1
	v_add_f32_dpp v66, v66, v66 quad_perm:[2,3,0,1] row_mask:0xf bank_mask:0xf bound_ctrl:1
	v_pk_mul_f32 v[62:63], v[138:139], v[132:133] op_sel_hi:[0,1]
	v_add_f32_dpp v58, v58, v58 row_half_mirror row_mask:0xf bank_mask:0xf bound_ctrl:1
	v_add_f32_dpp v66, v66, v66 row_half_mirror row_mask:0xf bank_mask:0xf bound_ctrl:1
	v_pk_fma_f32 v[62:63], v[92:93], v[128:129], v[62:63]
	v_add_f32_dpp v58, v58, v58 row_mirror row_mask:0xf bank_mask:0xf bound_ctrl:1
	v_add_f32_dpp v66, v66, v66 row_mirror row_mask:0xf bank_mask:0xf bound_ctrl:1
	v_pk_fma_f32 v[90:91], v[134:135], v[58:59], v[60:61] op_sel_hi:[1,0,1] neg_lo:[1,0,0] neg_hi:[1,0,0]
	v_pk_fma_f32 v[92:93], v[136:137], v[58:59], v[62:63] op_sel_hi:[1,0,1] neg_lo:[1,0,0] neg_hi:[1,0,0]
	v_cndmask_b32_e64 v67, v67, v66, s[40:41]
	s_waitcnt lgkmcnt(6)
	ds_read_b128 v[100:103], v49 offset:7936
	ds_read_b32 v116, v50 offset:8192
	ds_read_b128 v[108:111], v49 offset:8704
	ds_read_b128 v[104:107], v49 offset:8448
	ds_read_b128 v[112:115], v49 offset:8960
	ds_read_b128 v[96:99], v49 offset:7680
	v_pk_mul_f32 v[56:57], v[90:91], v[144:145]
	v_pk_mul_f32 v[64:65], v[120:121], v[92:93]
	v_pk_fma_f32 v[56:57], v[92:93], v[146:147], v[56:57]
	v_pk_fma_f32 v[64:65], v[118:119], v[90:91], v[64:65]
	v_add_f32_e32 v58, v56, v57
	v_add_f32_e32 v66, v64, v65
	v_pk_mul_f32 v[60:61], v[160:161], v[152:153] op_sel_hi:[0,1]
	v_add_f32_dpp v58, v58, v58 quad_perm:[1,0,3,2] row_mask:0xf bank_mask:0xf bound_ctrl:1
	v_add_f32_dpp v66, v66, v66 quad_perm:[1,0,3,2] row_mask:0xf bank_mask:0xf bound_ctrl:1
	v_pk_fma_f32 v[60:61], v[90:91], v[148:149], v[60:61]
	v_add_f32_dpp v58, v58, v58 quad_perm:[2,3,0,1] row_mask:0xf bank_mask:0xf bound_ctrl:1
	v_add_f32_dpp v66, v66, v66 quad_perm:[2,3,0,1] row_mask:0xf bank_mask:0xf bound_ctrl:1
	v_pk_mul_f32 v[62:63], v[160:161], v[154:155] op_sel_hi:[0,1]
	v_add_f32_dpp v58, v58, v58 row_half_mirror row_mask:0xf bank_mask:0xf bound_ctrl:1
	v_add_f32_dpp v66, v66, v66 row_half_mirror row_mask:0xf bank_mask:0xf bound_ctrl:1
	v_pk_fma_f32 v[62:63], v[92:93], v[150:151], v[62:63]
	v_add_f32_dpp v58, v58, v58 row_mirror row_mask:0xf bank_mask:0xf bound_ctrl:1
	v_add_f32_dpp v66, v66, v66 row_mirror row_mask:0xf bank_mask:0xf bound_ctrl:1
	v_pk_fma_f32 v[90:91], v[156:157], v[58:59], v[60:61] op_sel_hi:[1,0,1] neg_lo:[1,0,0] neg_hi:[1,0,0]
	v_pk_fma_f32 v[92:93], v[158:159], v[58:59], v[62:63] op_sel_hi:[1,0,1] neg_lo:[1,0,0] neg_hi:[1,0,0]
	v_cndmask_b32_e64 v67, v67, v66, s[42:43]
	s_waitcnt lgkmcnt(6)
	ds_read_b128 v[122:125], v49 offset:9472
	ds_read_b32 v138, v50 offset:9728
	ds_read_b128 v[130:133], v49 offset:10240
	ds_read_b128 v[126:129], v49 offset:9984
	ds_read_b128 v[134:137], v49 offset:10496
	ds_read_b128 v[118:121], v49 offset:9216
	v_pk_mul_f32 v[56:57], v[90:91], v[72:73]
	v_pk_mul_f32 v[64:65], v[142:143], v[92:93]
	v_pk_fma_f32 v[56:57], v[92:93], v[74:75], v[56:57]
	v_pk_fma_f32 v[64:65], v[140:141], v[90:91], v[64:65]
	v_add_f32_e32 v58, v56, v57
	v_add_f32_e32 v66, v64, v65
	v_pk_mul_f32 v[60:61], v[88:89], v[80:81] op_sel_hi:[0,1]
	v_add_f32_dpp v58, v58, v58 quad_perm:[1,0,3,2] row_mask:0xf bank_mask:0xf bound_ctrl:1
	v_add_f32_dpp v66, v66, v66 quad_perm:[1,0,3,2] row_mask:0xf bank_mask:0xf bound_ctrl:1
	v_pk_fma_f32 v[60:61], v[90:91], v[76:77], v[60:61]
	v_add_f32_dpp v58, v58, v58 quad_perm:[2,3,0,1] row_mask:0xf bank_mask:0xf bound_ctrl:1
	v_add_f32_dpp v66, v66, v66 quad_perm:[2,3,0,1] row_mask:0xf bank_mask:0xf bound_ctrl:1
	v_pk_mul_f32 v[62:63], v[88:89], v[82:83] op_sel_hi:[0,1]
	v_add_f32_dpp v58, v58, v58 row_half_mirror row_mask:0xf bank_mask:0xf bound_ctrl:1
	v_add_f32_dpp v66, v66, v66 row_half_mirror row_mask:0xf bank_mask:0xf bound_ctrl:1
	v_pk_fma_f32 v[62:63], v[92:93], v[78:79], v[62:63]
	v_add_f32_dpp v58, v58, v58 row_mirror row_mask:0xf bank_mask:0xf bound_ctrl:1
	v_add_f32_dpp v66, v66, v66 row_mirror row_mask:0xf bank_mask:0xf bound_ctrl:1
	v_pk_fma_f32 v[90:91], v[84:85], v[58:59], v[60:61] op_sel_hi:[1,0,1] neg_lo:[1,0,0] neg_hi:[1,0,0]
	v_pk_fma_f32 v[92:93], v[86:87], v[58:59], v[62:63] op_sel_hi:[1,0,1] neg_lo:[1,0,0] neg_hi:[1,0,0]
	v_cndmask_b32_e64 v67, v67, v66, s[44:45]
	s_waitcnt lgkmcnt(6)
; DI void scan_item(const Params& p, int item, char* smem) {
;     ...
;     for (int st = 0; st < 16; st++) {
;       StepIn nxt = cur;
;       if (st + 1 < 16) nxt = ldstep(base + (st + 1) * 6 * 64);
;       __builtin_amdgcn_sched_barrier(0);
;       f32x2 ra = {cur.r.x, cur.r.y}, rb = {cur.r.z, cur.r.w}, ka = {cur.k.x, cur.k.y}, kb = {cur.k.z, cur.k.w};
;       f32x2 wa = {cur.w.x, cur.w.y}, wb = {cur.w.z, cur.w.w}, da = {cur.d.x, cur.d.y}, db = {cur.d.z, cur.d.w};
;       f32x2 ba = {cur.b.x, cur.b.y}, bb2 = {cur.b.z, cur.b.w};
;       f32x2 pp = Sa * ka + Sb * kb;
;       float sa = allreduce16(pp.x + pp.y);
;       f32x2 vv2 = {cur.v, cur.v};
;       f32x2 sa2 = {sa, sa};
;       Sa = (Sa * wa + vv2 * da) - sa2 * ba;
;       Sb = (Sb * wb + vv2 * db) - sa2 * bb2;
;       f32x2 yy = Sa * ra + Sb * rb;
;       float y = allreduce16(yy.x + yy.y);
;       ykeep = (l16 == st) ? y : ykeep;
;       cur = nxt;
;     }
	ds_read_b128 v[144:147], v49 offset:11008
	ds_read_b32 v160, v50 offset:11264
	ds_read_b128 v[152:155], v49 offset:11776
	ds_read_b128 v[148:151], v49 offset:11520
	ds_read_b128 v[156:159], v49 offset:12032
	ds_read_b128 v[140:143], v49 offset:10752
	v_pk_mul_f32 v[56:57], v[90:91], v[100:101]
	v_pk_mul_f32 v[64:65], v[70:71], v[92:93]
	v_pk_fma_f32 v[56:57], v[92:93], v[102:103], v[56:57]
	v_pk_fma_f32 v[64:65], v[68:69], v[90:91], v[64:65]
	v_add_f32_e32 v58, v56, v57
	v_add_f32_e32 v66, v64, v65
	v_pk_mul_f32 v[60:61], v[116:117], v[108:109] op_sel_hi:[0,1]
	v_add_f32_dpp v58, v58, v58 quad_perm:[1,0,3,2] row_mask:0xf bank_mask:0xf bound_ctrl:1
	v_add_f32_dpp v66, v66, v66 quad_perm:[1,0,3,2] row_mask:0xf bank_mask:0xf bound_ctrl:1
	v_pk_fma_f32 v[60:61], v[90:91], v[104:105], v[60:61]
	v_add_f32_dpp v58, v58, v58 quad_perm:[2,3,0,1] row_mask:0xf bank_mask:0xf bound_ctrl:1
	v_add_f32_dpp v66, v66, v66 quad_perm:[2,3,0,1] row_mask:0xf bank_mask:0xf bound_ctrl:1
	v_pk_mul_f32 v[62:63], v[116:117], v[110:111] op_sel_hi:[0,1]
	v_add_f32_dpp v58, v58, v58 row_half_mirror row_mask:0xf bank_mask:0xf bound_ctrl:1
	v_add_f32_dpp v66, v66, v66 row_half_mirror row_mask:0xf bank_mask:0xf bound_ctrl:1
	v_pk_fma_f32 v[62:63], v[92:93], v[106:107], v[62:63]
	v_add_f32_dpp v58, v58, v58 row_mirror row_mask:0xf bank_mask:0xf bound_ctrl:1
	v_add_f32_dpp v66, v66, v66 row_mirror row_mask:0xf bank_mask:0xf bound_ctrl:1
	v_pk_fma_f32 v[90:91], v[112:113], v[58:59], v[60:61] op_sel_hi:[1,0,1] neg_lo:[1,0,0] neg_hi:[1,0,0]
	v_pk_fma_f32 v[92:93], v[114:115], v[58:59], v[62:63] op_sel_hi:[1,0,1] neg_lo:[1,0,0] neg_hi:[1,0,0]
	v_cndmask_b32_e64 v67, v67, v66, s[46:47]
	s_waitcnt lgkmcnt(6)
	ds_read_b128 v[72:75], v49 offset:12544
	ds_read_b32 v88, v50 offset:12800
	ds_read_b128 v[80:83], v49 offset:13312
	ds_read_b128 v[76:79], v49 offset:13056
	ds_read_b128 v[84:87], v49 offset:13568
	ds_read_b128 v[68:71], v49 offset:12288
	v_pk_mul_f32 v[56:57], v[90:91], v[122:123]
	v_pk_mul_f32 v[64:65], v[98:99], v[92:93]
	v_pk_fma_f32 v[56:57], v[92:93], v[124:125], v[56:57]
	v_pk_fma_f32 v[64:65], v[96:97], v[90:91], v[64:65]
	v_add_f32_e32 v58, v56, v57
	v_add_f32_e32 v66, v64, v65
	v_pk_mul_f32 v[60:61], v[138:139], v[130:131] op_sel_hi:[0,1]
	v_add_f32_dpp v58, v58, v58 quad_perm:[1,0,3,2] row_mask:0xf bank_mask:0xf bound_ctrl:1
	v_add_f32_dpp v66, v66, v66 quad_perm:[1,0,3,2] row_mask:0xf bank_mask:0xf bound_ctrl:1
	v_pk_fma_f32 v[60:61], v[90:91], v[126:127], v[60:61]
	v_add_f32_dpp v58, v58, v58 quad_perm:[2,3,0,1] row_mask:0xf bank_mask:0xf bound_ctrl:1
	v_add_f32_dpp v66, v66, v66 quad_perm:[2,3,0,1] row_mask:0xf bank_mask:0xf bound_ctrl:1
	v_pk_mul_f32 v[62:63], v[138:139], v[132:133] op_sel_hi:[0,1]
	v_add_f32_dpp v58, v58, v58 row_half_mirror row_mask:0xf bank_mask:0xf bound_ctrl:1
	v_add_f32_dpp v66, v66, v66 row_half_mirror row_mask:0xf bank_mask:0xf bound_ctrl:1
	v_pk_fma_f32 v[62:63], v[92:93], v[128:129], v[62:63]
	v_add_f32_dpp v58, v58, v58 row_mirror row_mask:0xf bank_mask:0xf bound_ctrl:1
	v_add_f32_dpp v66, v66, v66 row_mirror row_mask:0xf bank_mask:0xf bound_ctrl:1
	v_pk_fma_f32 v[90:91], v[134:135], v[58:59], v[60:61] op_sel_hi:[1,0,1] neg_lo:[1,0,0] neg_hi:[1,0,0]
	v_pk_fma_f32 v[92:93], v[136:137], v[58:59], v[62:63] op_sel_hi:[1,0,1] neg_lo:[1,0,0] neg_hi:[1,0,0]
	v_cndmask_b32_e64 v67, v67, v66, s[48:49]
	s_waitcnt lgkmcnt(6)
	ds_read_b128 v[100:103], v49 offset:14080
	ds_read_b32 v116, v50 offset:14336
	ds_read_b128 v[108:111], v49 offset:14848
	ds_read_b128 v[104:107], v49 offset:14592
	ds_read_b128 v[112:115], v49 offset:15104
	ds_read_b128 v[96:99], v49 offset:13824
	v_pk_mul_f32 v[56:57], v[90:91], v[144:145]
	v_pk_mul_f32 v[64:65], v[120:121], v[92:93]
	v_pk_fma_f32 v[56:57], v[92:93], v[146:147], v[56:57]
	v_pk_fma_f32 v[64:65], v[118:119], v[90:91], v[64:65]
	v_add_f32_e32 v58, v56, v57
	v_add_f32_e32 v66, v64, v65
	v_pk_mul_f32 v[60:61], v[160:161], v[152:153] op_sel_hi:[0,1]
	v_add_f32_dpp v58, v58, v58 quad_perm:[1,0,3,2] row_mask:0xf bank_mask:0xf bound_ctrl:1
	v_add_f32_dpp v66, v66, v66 quad_perm:[1,0,3,2] row_mask:0xf bank_mask:0xf bound_ctrl:1
	v_pk_fma_f32 v[60:61], v[90:91], v[148:149], v[60:61]
	v_add_f32_dpp v58, v58, v58 quad_perm:[2,3,0,1] row_mask:0xf bank_mask:0xf bound_ctrl:1
	v_add_f32_dpp v66, v66, v66 quad_perm:[2,3,0,1] row_mask:0xf bank_mask:0xf bound_ctrl:1
	v_pk_mul_f32 v[62:63], v[160:161], v[154:155] op_sel_hi:[0,1]
	v_add_f32_dpp v58, v58, v58 row_half_mirror row_mask:0xf bank_mask:0xf bound_ctrl:1
	v_add_f32_dpp v66, v66, v66 row_half_mirror row_mask:0xf bank_mask:0xf bound_ctrl:1
	v_pk_fma_f32 v[62:63], v[92:93], v[150:151], v[62:63]
	v_add_f32_dpp v58, v58, v58 row_mirror row_mask:0xf bank_mask:0xf bound_ctrl:1
	v_add_f32_dpp v66, v66, v66 row_mirror row_mask:0xf bank_mask:0xf bound_ctrl:1
	v_pk_fma_f32 v[90:91], v[156:157], v[58:59], v[60:61] op_sel_hi:[1,0,1] neg_lo:[1,0,0] neg_hi:[1,0,0]
	v_pk_fma_f32 v[92:93], v[158:159], v[58:59], v[62:63] op_sel_hi:[1,0,1] neg_lo:[1,0,0] neg_hi:[1,0,0]
	v_cndmask_b32_e64 v67, v67, v66, s[50:51]
	s_waitcnt lgkmcnt(6)
; DI void scan_item(const Params& p, int item, char* smem) {
;     ...
;     for (int st = 0; st < 16; st++) {
;       StepIn nxt = cur;
;       if (st + 1 < 16) nxt = ldstep(base + (st + 1) * 6 * 64);
;       __builtin_amdgcn_sched_barrier(0);
;       f32x2 ra = {cur.r.x, cur.r.y}, rb = {cur.r.z, cur.r.w}, ka = {cur.k.x, cur.k.y}, kb = {cur.k.z, cur.k.w};
;       f32x2 wa = {cur.w.x, cur.w.y}, wb = {cur.w.z, cur.w.w}, da = {cur.d.x, cur.d.y}, db = {cur.d.z, cur.d.w};
;       f32x2 ba = {cur.b.x, cur.b.y}, bb2 = {cur.b.z, cur.b.w};
;       f32x2 pp = Sa * ka + Sb * kb;
;       float sa = allreduce16(pp.x + pp.y);
;       f32x2 vv2 = {cur.v, cur.v};
;       f32x2 sa2 = {sa, sa};
;       Sa = (Sa * wa + vv2 * da) - sa2 * ba;
;       Sb = (Sb * wb + vv2 * db) - sa2 * bb2;
;       f32x2 yy = Sa * ra + Sb * rb;
;       float y = allreduce16(yy.x + yy.y);
;       ykeep = (l16 == st) ? y : ykeep;
;       cur = nxt;
;     }
	ds_read_b128 v[122:125], v49 offset:15616
	ds_read_b32 v138, v50 offset:15872
	ds_read_b128 v[130:133], v49 offset:16384
	ds_read_b128 v[126:129], v49 offset:16128
	ds_read_b128 v[134:137], v49 offset:16640
	ds_read_b128 v[118:121], v49 offset:15360
	v_pk_mul_f32 v[56:57], v[90:91], v[72:73]
	v_pk_mul_f32 v[64:65], v[142:143], v[92:93]
	v_pk_fma_f32 v[56:57], v[92:93], v[74:75], v[56:57]
	v_pk_fma_f32 v[64:65], v[140:141], v[90:91], v[64:65]
	v_add_f32_e32 v58, v56, v57
	v_add_f32_e32 v66, v64, v65
	v_pk_mul_f32 v[60:61], v[88:89], v[80:81] op_sel_hi:[0,1]
	v_add_f32_dpp v58, v58, v58 quad_perm:[1,0,3,2] row_mask:0xf bank_mask:0xf bound_ctrl:1
	v_add_f32_dpp v66, v66, v66 quad_perm:[1,0,3,2] row_mask:0xf bank_mask:0xf bound_ctrl:1
	v_pk_fma_f32 v[60:61], v[90:91], v[76:77], v[60:61]
	v_add_f32_dpp v58, v58, v58 quad_perm:[2,3,0,1] row_mask:0xf bank_mask:0xf bound_ctrl:1
	v_add_f32_dpp v66, v66, v66 quad_perm:[2,3,0,1] row_mask:0xf bank_mask:0xf bound_ctrl:1
	v_pk_mul_f32 v[62:63], v[88:89], v[82:83] op_sel_hi:[0,1]
	v_add_f32_dpp v58, v58, v58 row_half_mirror row_mask:0xf bank_mask:0xf bound_ctrl:1
	v_add_f32_dpp v66, v66, v66 row_half_mirror row_mask:0xf bank_mask:0xf bound_ctrl:1
	v_pk_fma_f32 v[62:63], v[92:93], v[78:79], v[62:63]
	v_add_f32_dpp v58, v58, v58 row_mirror row_mask:0xf bank_mask:0xf bound_ctrl:1
	v_add_f32_dpp v66, v66, v66 row_mirror row_mask:0xf bank_mask:0xf bound_ctrl:1
	v_pk_fma_f32 v[90:91], v[84:85], v[58:59], v[60:61] op_sel_hi:[1,0,1] neg_lo:[1,0,0] neg_hi:[1,0,0]
	v_pk_fma_f32 v[92:93], v[86:87], v[58:59], v[62:63] op_sel_hi:[1,0,1] neg_lo:[1,0,0] neg_hi:[1,0,0]
	v_cndmask_b32_e64 v67, v67, v66, s[52:53]
	s_waitcnt lgkmcnt(6)
	ds_read_b128 v[144:147], v49 offset:17152
	ds_read_b32 v160, v50 offset:17408
	ds_read_b128 v[152:155], v49 offset:17920
	ds_read_b128 v[148:151], v49 offset:17664
	ds_read_b128 v[156:159], v49 offset:18176
	ds_read_b128 v[140:143], v49 offset:16896
	v_pk_mul_f32 v[56:57], v[90:91], v[100:101]
	v_pk_mul_f32 v[64:65], v[70:71], v[92:93]
	v_pk_fma_f32 v[56:57], v[92:93], v[102:103], v[56:57]
	v_pk_fma_f32 v[64:65], v[68:69], v[90:91], v[64:65]
	v_add_f32_e32 v58, v56, v57
	v_add_f32_e32 v66, v64, v65
	v_pk_mul_f32 v[60:61], v[116:117], v[108:109] op_sel_hi:[0,1]
	v_add_f32_dpp v58, v58, v58 quad_perm:[1,0,3,2] row_mask:0xf bank_mask:0xf bound_ctrl:1
	v_add_f32_dpp v66, v66, v66 quad_perm:[1,0,3,2] row_mask:0xf bank_mask:0xf bound_ctrl:1
	v_pk_fma_f32 v[60:61], v[90:91], v[104:105], v[60:61]
	v_add_f32_dpp v58, v58, v58 quad_perm:[2,3,0,1] row_mask:0xf bank_mask:0xf bound_ctrl:1
	v_add_f32_dpp v66, v66, v66 quad_perm:[2,3,0,1] row_mask:0xf bank_mask:0xf bound_ctrl:1
	v_pk_mul_f32 v[62:63], v[116:117], v[110:111] op_sel_hi:[0,1]
	v_add_f32_dpp v58, v58, v58 row_half_mirror row_mask:0xf bank_mask:0xf bound_ctrl:1
	v_add_f32_dpp v66, v66, v66 row_half_mirror row_mask:0xf bank_mask:0xf bound_ctrl:1
	v_pk_fma_f32 v[62:63], v[92:93], v[106:107], v[62:63]
	v_add_f32_dpp v58, v58, v58 row_mirror row_mask:0xf bank_mask:0xf bound_ctrl:1
	v_add_f32_dpp v66, v66, v66 row_mirror row_mask:0xf bank_mask:0xf bound_ctrl:1
	v_pk_fma_f32 v[90:91], v[112:113], v[58:59], v[60:61] op_sel_hi:[1,0,1] neg_lo:[1,0,0] neg_hi:[1,0,0]
	v_pk_fma_f32 v[92:93], v[114:115], v[58:59], v[62:63] op_sel_hi:[1,0,1] neg_lo:[1,0,0] neg_hi:[1,0,0]
	v_cndmask_b32_e64 v67, v67, v66, s[54:55]
	s_waitcnt lgkmcnt(6)
	ds_read_b128 v[72:75], v49 offset:18688
	ds_read_b32 v88, v50 offset:18944
	ds_read_b128 v[80:83], v49 offset:19456
	ds_read_b128 v[76:79], v49 offset:19200
	ds_read_b128 v[84:87], v49 offset:19712
	ds_read_b128 v[68:71], v49 offset:18432
	v_pk_mul_f32 v[56:57], v[90:91], v[122:123]
	v_pk_mul_f32 v[64:65], v[98:99], v[92:93]
	v_pk_fma_f32 v[56:57], v[92:93], v[124:125], v[56:57]
	v_pk_fma_f32 v[64:65], v[96:97], v[90:91], v[64:65]
	v_add_f32_e32 v58, v56, v57
	v_add_f32_e32 v66, v64, v65
	v_pk_mul_f32 v[60:61], v[138:139], v[130:131] op_sel_hi:[0,1]
	v_add_f32_dpp v58, v58, v58 quad_perm:[1,0,3,2] row_mask:0xf bank_mask:0xf bound_ctrl:1
	v_add_f32_dpp v66, v66, v66 quad_perm:[1,0,3,2] row_mask:0xf bank_mask:0xf bound_ctrl:1
	v_pk_fma_f32 v[60:61], v[90:91], v[126:127], v[60:61]
	v_add_f32_dpp v58, v58, v58 quad_perm:[2,3,0,1] row_mask:0xf bank_mask:0xf bound_ctrl:1
	v_add_f32_dpp v66, v66, v66 quad_perm:[2,3,0,1] row_mask:0xf bank_mask:0xf bound_ctrl:1
	v_pk_mul_f32 v[62:63], v[138:139], v[132:133] op_sel_hi:[0,1]
	v_add_f32_dpp v58, v58, v58 row_half_mirror row_mask:0xf bank_mask:0xf bound_ctrl:1
	v_add_f32_dpp v66, v66, v66 row_half_mirror row_mask:0xf bank_mask:0xf bound_ctrl:1
	v_pk_fma_f32 v[62:63], v[92:93], v[128:129], v[62:63]
	v_add_f32_dpp v58, v58, v58 row_mirror row_mask:0xf bank_mask:0xf bound_ctrl:1
	v_add_f32_dpp v66, v66, v66 row_mirror row_mask:0xf bank_mask:0xf bound_ctrl:1
	v_pk_fma_f32 v[90:91], v[134:135], v[58:59], v[60:61] op_sel_hi:[1,0,1] neg_lo:[1,0,0] neg_hi:[1,0,0]
	v_pk_fma_f32 v[92:93], v[136:137], v[58:59], v[62:63] op_sel_hi:[1,0,1] neg_lo:[1,0,0] neg_hi:[1,0,0]
	v_cndmask_b32_e64 v67, v67, v66, s[56:57]
	s_waitcnt lgkmcnt(6)
; DI void scan_item(const Params& p, int item, char* smem) {
;     ...
;     for (int st = 0; st < 16; st++) {
;       StepIn nxt = cur;
;       if (st + 1 < 16) nxt = ldstep(base + (st + 1) * 6 * 64);
;       __builtin_amdgcn_sched_barrier(0);
;       f32x2 ra = {cur.r.x, cur.r.y}, rb = {cur.r.z, cur.r.w}, ka = {cur.k.x, cur.k.y}, kb = {cur.k.z, cur.k.w};
;       f32x2 wa = {cur.w.x, cur.w.y}, wb = {cur.w.z, cur.w.w}, da = {cur.d.x, cur.d.y}, db = {cur.d.z, cur.d.w};
;       f32x2 ba = {cur.b.x, cur.b.y}, bb2 = {cur.b.z, cur.b.w};
;       f32x2 pp = Sa * ka + Sb * kb;
;       float sa = allreduce16(pp.x + pp.y);
;       f32x2 vv2 = {cur.v, cur.v};
;       f32x2 sa2 = {sa, sa};
;       Sa = (Sa * wa + vv2 * da) - sa2 * ba;
;       Sb = (Sb * wb + vv2 * db) - sa2 * bb2;
;       f32x2 yy = Sa * ra + Sb * rb;
;       float y = allreduce16(yy.x + yy.y);
;       ykeep = (l16 == st) ? y : ykeep;
;       cur = nxt;
;     }
	ds_read_b128 v[100:103], v49 offset:20224
	ds_read_b32 v116, v50 offset:20480
	ds_read_b128 v[108:111], v49 offset:20992
	ds_read_b128 v[104:107], v49 offset:20736
	ds_read_b128 v[112:115], v49 offset:21248
	ds_read_b128 v[96:99], v49 offset:19968
	v_pk_mul_f32 v[56:57], v[90:91], v[144:145]
	v_pk_mul_f32 v[64:65], v[120:121], v[92:93]
	v_pk_fma_f32 v[56:57], v[92:93], v[146:147], v[56:57]
	v_pk_fma_f32 v[64:65], v[118:119], v[90:91], v[64:65]
	v_add_f32_e32 v58, v56, v57
	v_add_f32_e32 v66, v64, v65
	v_pk_mul_f32 v[60:61], v[160:161], v[152:153] op_sel_hi:[0,1]
	v_add_f32_dpp v58, v58, v58 quad_perm:[1,0,3,2] row_mask:0xf bank_mask:0xf bound_ctrl:1
	v_add_f32_dpp v66, v66, v66 quad_perm:[1,0,3,2] row_mask:0xf bank_mask:0xf bound_ctrl:1
	v_pk_fma_f32 v[60:61], v[90:91], v[148:149], v[60:61]
	v_add_f32_dpp v58, v58, v58 quad_perm:[2,3,0,1] row_mask:0xf bank_mask:0xf bound_ctrl:1
	v_add_f32_dpp v66, v66, v66 quad_perm:[2,3,0,1] row_mask:0xf bank_mask:0xf bound_ctrl:1
	v_pk_mul_f32 v[62:63], v[160:161], v[154:155] op_sel_hi:[0,1]
	v_add_f32_dpp v58, v58, v58 row_half_mirror row_mask:0xf bank_mask:0xf bound_ctrl:1
	v_add_f32_dpp v66, v66, v66 row_half_mirror row_mask:0xf bank_mask:0xf bound_ctrl:1
	v_pk_fma_f32 v[62:63], v[92:93], v[150:151], v[62:63]
	v_add_f32_dpp v58, v58, v58 row_mirror row_mask:0xf bank_mask:0xf bound_ctrl:1
	v_add_f32_dpp v66, v66, v66 row_mirror row_mask:0xf bank_mask:0xf bound_ctrl:1
	v_pk_fma_f32 v[90:91], v[156:157], v[58:59], v[60:61] op_sel_hi:[1,0,1] neg_lo:[1,0,0] neg_hi:[1,0,0]
	v_pk_fma_f32 v[92:93], v[158:159], v[58:59], v[62:63] op_sel_hi:[1,0,1] neg_lo:[1,0,0] neg_hi:[1,0,0]
	v_cndmask_b32_e64 v67, v67, v66, s[58:59]
	s_waitcnt lgkmcnt(6)
	ds_read_b128 v[122:125], v49 offset:21760
	ds_read_b32 v138, v50 offset:22016
	ds_read_b128 v[130:133], v49 offset:22528
	ds_read_b128 v[126:129], v49 offset:22272
	ds_read_b128 v[134:137], v49 offset:22784
	ds_read_b128 v[118:121], v49 offset:21504
	v_pk_mul_f32 v[56:57], v[90:91], v[72:73]
	v_pk_mul_f32 v[64:65], v[142:143], v[92:93]
	v_pk_fma_f32 v[56:57], v[92:93], v[74:75], v[56:57]
	v_pk_fma_f32 v[64:65], v[140:141], v[90:91], v[64:65]
	v_add_f32_e32 v58, v56, v57
	v_add_f32_e32 v66, v64, v65
	v_pk_mul_f32 v[60:61], v[88:89], v[80:81] op_sel_hi:[0,1]
	v_add_f32_dpp v58, v58, v58 quad_perm:[1,0,3,2] row_mask:0xf bank_mask:0xf bound_ctrl:1
	v_add_f32_dpp v66, v66, v66 quad_perm:[1,0,3,2] row_mask:0xf bank_mask:0xf bound_ctrl:1
	v_pk_fma_f32 v[60:61], v[90:91], v[76:77], v[60:61]
	v_add_f32_dpp v58, v58, v58 quad_perm:[2,3,0,1] row_mask:0xf bank_mask:0xf bound_ctrl:1
	v_add_f32_dpp v66, v66, v66 quad_perm:[2,3,0,1] row_mask:0xf bank_mask:0xf bound_ctrl:1
	v_pk_mul_f32 v[62:63], v[88:89], v[82:83] op_sel_hi:[0,1]
	v_add_f32_dpp v58, v58, v58 row_half_mirror row_mask:0xf bank_mask:0xf bound_ctrl:1
	v_add_f32_dpp v66, v66, v66 row_half_mirror row_mask:0xf bank_mask:0xf bound_ctrl:1
	v_pk_fma_f32 v[62:63], v[92:93], v[78:79], v[62:63]
	v_add_f32_dpp v58, v58, v58 row_mirror row_mask:0xf bank_mask:0xf bound_ctrl:1
	v_add_f32_dpp v66, v66, v66 row_mirror row_mask:0xf bank_mask:0xf bound_ctrl:1
	v_pk_fma_f32 v[90:91], v[84:85], v[58:59], v[60:61] op_sel_hi:[1,0,1] neg_lo:[1,0,0] neg_hi:[1,0,0]
	v_pk_fma_f32 v[92:93], v[86:87], v[58:59], v[62:63] op_sel_hi:[1,0,1] neg_lo:[1,0,0] neg_hi:[1,0,0]
	v_cndmask_b32_e64 v67, v67, v66, s[60:61]
	s_waitcnt lgkmcnt(6)
	ds_read_b128 v[144:147], v49 offset:23296
	ds_read_b32 v160, v50 offset:23552
	ds_read_b128 v[152:155], v49 offset:24064
	ds_read_b128 v[148:151], v49 offset:23808
	ds_read_b128 v[156:159], v49 offset:24320
	ds_read_b128 v[140:143], v49 offset:23040
	v_pk_mul_f32 v[56:57], v[90:91], v[100:101]
	v_pk_mul_f32 v[64:65], v[70:71], v[92:93]
	v_pk_fma_f32 v[56:57], v[92:93], v[102:103], v[56:57]
	v_pk_fma_f32 v[64:65], v[68:69], v[90:91], v[64:65]
	v_add_f32_e32 v58, v56, v57
	v_add_f32_e32 v66, v64, v65
	v_pk_mul_f32 v[60:61], v[116:117], v[108:109] op_sel_hi:[0,1]
	v_add_f32_dpp v58, v58, v58 quad_perm:[1,0,3,2] row_mask:0xf bank_mask:0xf bound_ctrl:1
	v_add_f32_dpp v66, v66, v66 quad_perm:[1,0,3,2] row_mask:0xf bank_mask:0xf bound_ctrl:1
	v_pk_fma_f32 v[60:61], v[90:91], v[104:105], v[60:61]
	v_add_f32_dpp v58, v58, v58 quad_perm:[2,3,0,1] row_mask:0xf bank_mask:0xf bound_ctrl:1
	v_add_f32_dpp v66, v66, v66 quad_perm:[2,3,0,1] row_mask:0xf bank_mask:0xf bound_ctrl:1
	v_pk_mul_f32 v[62:63], v[116:117], v[110:111] op_sel_hi:[0,1]
	v_add_f32_dpp v58, v58, v58 row_half_mirror row_mask:0xf bank_mask:0xf bound_ctrl:1
	v_add_f32_dpp v66, v66, v66 row_half_mirror row_mask:0xf bank_mask:0xf bound_ctrl:1
	v_pk_fma_f32 v[62:63], v[92:93], v[106:107], v[62:63]
	v_add_f32_dpp v58, v58, v58 row_mirror row_mask:0xf bank_mask:0xf bound_ctrl:1
	v_add_f32_dpp v66, v66, v66 row_mirror row_mask:0xf bank_mask:0xf bound_ctrl:1
	v_pk_fma_f32 v[90:91], v[112:113], v[58:59], v[60:61] op_sel_hi:[1,0,1] neg_lo:[1,0,0] neg_hi:[1,0,0]
	v_pk_fma_f32 v[92:93], v[114:115], v[58:59], v[62:63] op_sel_hi:[1,0,1] neg_lo:[1,0,0] neg_hi:[1,0,0]
	v_cndmask_b32_e64 v67, v67, v66, s[62:63]
	s_waitcnt lgkmcnt(6)
; DI void scan_item(const Params& p, int item, char* smem) {
;     ...
;   auto lstore = [&](int buf) {
; #pragma unroll
;     for (int i = 0; i < 3; i++) {
;       int id = tid + i * 256;
;       int st = id / 48, rem = id % 48, vec = rem >> 3, part = rem & 7;
;       h8 hv = __builtin_bit_cast(h8, rg_[i]);
;       f8 fv = __builtin_convertvector(hv, f8);
;       float* d = sIn + ((buf * 16 + st) * 6 + vec) * 64 + part * 8;
;       *(f32x4v*)d = f32x4v{fv[0], fv[1], fv[2], fv[3]};
;       *(f32x4v*)(d + 4) = f32x4v{fv[4], fv[5], fv[6], fv[7]};
;     }
;   };
;     ...
;     for (int st = 0; st < 16; st++) {
;       StepIn nxt = cur;
;       if (st + 1 < 16) nxt = ldstep(base + (st + 1) * 6 * 64);
;       __builtin_amdgcn_sched_barrier(0);
;       f32x2 ra = {cur.r.x, cur.r.y}, rb = {cur.r.z, cur.r.w}, ka = {cur.k.x, cur.k.y}, kb = {cur.k.z, cur.k.w};
;       f32x2 wa = {cur.w.x, cur.w.y}, wb = {cur.w.z, cur.w.w}, da = {cur.d.x, cur.d.y}, db = {cur.d.z, cur.d.w};
;       f32x2 ba = {cur.b.x, cur.b.y}, bb2 = {cur.b.z, cur.b.w};
;       f32x2 pp = Sa * ka + Sb * kb;
;       float sa = allreduce16(pp.x + pp.y);
;       f32x2 vv2 = {cur.v, cur.v};
;       f32x2 sa2 = {sa, sa};
;       Sa = (Sa * wa + vv2 * da) - sa2 * ba;
;       Sb = (Sb * wb + vv2 * db) - sa2 * bb2;
;       f32x2 yy = Sa * ra + Sb * rb;
;       float y = allreduce16(yy.x + yy.y);
;       ykeep = (l16 == st) ? y : ykeep;
;       cur = nxt;
;     }
;     { _Float16 yh = (_Float16)ykeep; yb[(long)tof(ci * 16 + l16) * 256 + rowl] = __builtin_bit_cast(u16, yh); }
;     if (ci + 1 < nch) lstore((ci + 1) & 1);
;     __syncthreads();
;   }
	v_pk_mul_f32 v[56:57], v[90:91], v[122:123]
	v_pk_mul_f32 v[64:65], v[98:99], v[92:93]
	v_pk_fma_f32 v[56:57], v[92:93], v[124:125], v[56:57]
	v_pk_fma_f32 v[64:65], v[96:97], v[90:91], v[64:65]
	v_add_f32_e32 v58, v56, v57
	v_add_f32_e32 v66, v64, v65
	v_pk_mul_f32 v[60:61], v[138:139], v[130:131] op_sel_hi:[0,1]
	v_add_f32_dpp v58, v58, v58 quad_perm:[1,0,3,2] row_mask:0xf bank_mask:0xf bound_ctrl:1
	v_add_f32_dpp v66, v66, v66 quad_perm:[1,0,3,2] row_mask:0xf bank_mask:0xf bound_ctrl:1
	v_pk_fma_f32 v[60:61], v[90:91], v[126:127], v[60:61]
	v_add_f32_dpp v58, v58, v58 quad_perm:[2,3,0,1] row_mask:0xf bank_mask:0xf bound_ctrl:1
	v_add_f32_dpp v66, v66, v66 quad_perm:[2,3,0,1] row_mask:0xf bank_mask:0xf bound_ctrl:1
	v_pk_mul_f32 v[62:63], v[138:139], v[132:133] op_sel_hi:[0,1]
	v_add_f32_dpp v58, v58, v58 row_half_mirror row_mask:0xf bank_mask:0xf bound_ctrl:1
	v_add_f32_dpp v66, v66, v66 row_half_mirror row_mask:0xf bank_mask:0xf bound_ctrl:1
	v_pk_fma_f32 v[62:63], v[92:93], v[128:129], v[62:63]
	v_add_f32_dpp v58, v58, v58 row_mirror row_mask:0xf bank_mask:0xf bound_ctrl:1
	v_add_f32_dpp v66, v66, v66 row_mirror row_mask:0xf bank_mask:0xf bound_ctrl:1
	v_pk_fma_f32 v[90:91], v[134:135], v[58:59], v[60:61] op_sel_hi:[1,0,1] neg_lo:[1,0,0] neg_hi:[1,0,0]
	v_pk_fma_f32 v[92:93], v[136:137], v[58:59], v[62:63] op_sel_hi:[1,0,1] neg_lo:[1,0,0] neg_hi:[1,0,0]
	v_cndmask_b32_e64 v67, v67, v66, s[64:65]
	s_waitcnt lgkmcnt(0)
	v_pk_mul_f32 v[56:57], v[90:91], v[144:145]
	v_pk_mul_f32 v[64:65], v[120:121], v[92:93]
	v_pk_fma_f32 v[56:57], v[92:93], v[146:147], v[56:57]
	v_pk_fma_f32 v[64:65], v[118:119], v[90:91], v[64:65]
	v_add_f32_e32 v58, v56, v57
	v_add_f32_e32 v66, v64, v65
	v_pk_mul_f32 v[60:61], v[160:161], v[152:153] op_sel_hi:[0,1]
	v_add_f32_dpp v58, v58, v58 quad_perm:[1,0,3,2] row_mask:0xf bank_mask:0xf bound_ctrl:1
	v_add_f32_dpp v66, v66, v66 quad_perm:[1,0,3,2] row_mask:0xf bank_mask:0xf bound_ctrl:1
	v_pk_fma_f32 v[60:61], v[90:91], v[148:149], v[60:61]
	v_add_f32_dpp v58, v58, v58 quad_perm:[2,3,0,1] row_mask:0xf bank_mask:0xf bound_ctrl:1
	v_add_f32_dpp v66, v66, v66 quad_perm:[2,3,0,1] row_mask:0xf bank_mask:0xf bound_ctrl:1
	v_pk_mul_f32 v[62:63], v[160:161], v[154:155] op_sel_hi:[0,1]
	v_add_f32_dpp v58, v58, v58 row_half_mirror row_mask:0xf bank_mask:0xf bound_ctrl:1
	v_add_f32_dpp v66, v66, v66 row_half_mirror row_mask:0xf bank_mask:0xf bound_ctrl:1
	v_pk_fma_f32 v[62:63], v[92:93], v[150:151], v[62:63]
	v_add_f32_dpp v58, v58, v58 row_mirror row_mask:0xf bank_mask:0xf bound_ctrl:1
	v_add_f32_dpp v66, v66, v66 row_mirror row_mask:0xf bank_mask:0xf bound_ctrl:1
	v_pk_fma_f32 v[90:91], v[156:157], v[58:59], v[60:61] op_sel_hi:[1,0,1] neg_lo:[1,0,0] neg_hi:[1,0,0]
	v_pk_fma_f32 v[92:93], v[158:159], v[58:59], v[62:63] op_sel_hi:[1,0,1] neg_lo:[1,0,0] neg_hi:[1,0,0]
	v_cndmask_b32_e64 v67, v67, v66, s[66:67]
	s_nop 0
	v_pk_mul_f32 v[64:65], v[142:143], v[92:93]
	s_cmpk_gt_u32 s26, 0xff
	s_movk_i32 s12, 0x11ff
	s_cselect_b32 s12, s12, 0xff
	v_pk_fma_f32 v[64:65], v[140:141], v[90:91], v[64:65]
	s_sub_i32 s12, s12, s26
	v_add_u32_e32 v46, s26, v36
	v_add_f32_e32 v66, v64, v65
	v_sub_u32_e32 v47, s12, v36
	v_cndmask_b32_e64 v46, v47, v46, s[36:37]
	v_add_f32_dpp v66, v66, v66 quad_perm:[1,0,3,2] row_mask:0xf bank_mask:0xf bound_ctrl:1
	v_mov_b32_e32 v47, 0
	v_lshlrev_b64 v[46:47], 9, v[46:47]
	v_add_f32_dpp v66, v66, v66 quad_perm:[2,3,0,1] row_mask:0xf bank_mask:0xf bound_ctrl:1
	v_lshl_add_u64 v[46:47], v[30:31], 0, v[46:47]
	s_nop 0
	v_add_f32_dpp v66, v66, v66 row_half_mirror row_mask:0xf bank_mask:0xf bound_ctrl:1
	s_nop 1
	v_add_f32_dpp v66, v66, v66 row_mirror row_mask:0xf bank_mask:0xf bound_ctrl:1
	v_cndmask_b32_e64 v67, v67, v66, s[68:69]
	v_cvt_f16_f32_e32 v45, v67
	global_store_short v[46:47], v45, off
	s_waitcnt vmcnt(6)
	v_cvt_f32_f16_e32 v40, v0
	v_cvt_f32_f16_sdwa v41, v0 dst_sel:DWORD dst_unused:UNUSED_PAD src0_sel:WORD_1
	v_cvt_f32_f16_e32 v42, v1
	v_cvt_f32_f16_sdwa v43, v1 dst_sel:DWORD dst_unused:UNUSED_PAD src0_sel:WORD_1
	v_cvt_f32_f16_e32 v44, v2
	v_cvt_f32_f16_sdwa v45, v2 dst_sel:DWORD dst_unused:UNUSED_PAD src0_sel:WORD_1
	v_cvt_f32_f16_e32 v46, v3
	v_cvt_f32_f16_sdwa v47, v3 dst_sel:DWORD dst_unused:UNUSED_PAD src0_sel:WORD_1
	ds_write_b128 v32, v[40:43] offset:24576
	ds_write_b128 v32, v[44:47] offset:24592
	s_waitcnt vmcnt(5)
	v_cvt_f32_f16_e32 v40, v4
	v_cvt_f32_f16_sdwa v41, v4 dst_sel:DWORD dst_unused:UNUSED_PAD src0_sel:WORD_1
	v_cvt_f32_f16_e32 v42, v5
	v_cvt_f32_f16_sdwa v43, v5 dst_sel:DWORD dst_unused:UNUSED_PAD src0_sel:WORD_1
	v_cvt_f32_f16_e32 v44, v6
	v_cvt_f32_f16_sdwa v45, v6 dst_sel:DWORD dst_unused:UNUSED_PAD src0_sel:WORD_1
	v_cvt_f32_f16_e32 v46, v7
	v_cvt_f32_f16_sdwa v47, v7 dst_sel:DWORD dst_unused:UNUSED_PAD src0_sel:WORD_1
	ds_write_b128 v33, v[40:43] offset:24576
	ds_write_b128 v33, v[44:47] offset:24592
	s_waitcnt vmcnt(4)
	v_cvt_f32_f16_e32 v40, v8
	v_cvt_f32_f16_sdwa v41, v8 dst_sel:DWORD dst_unused:UNUSED_PAD src0_sel:WORD_1
	v_cvt_f32_f16_e32 v42, v9
	v_cvt_f32_f16_sdwa v43, v9 dst_sel:DWORD dst_unused:UNUSED_PAD src0_sel:WORD_1
	v_cvt_f32_f16_e32 v44, v10
	v_cvt_f32_f16_sdwa v45, v10 dst_sel:DWORD dst_unused:UNUSED_PAD src0_sel:WORD_1
	v_cvt_f32_f16_e32 v46, v11
	v_cvt_f32_f16_sdwa v47, v11 dst_sel:DWORD dst_unused:UNUSED_PAD src0_sel:WORD_1
	ds_write_b128 v34, v[40:43] offset:24576
	ds_write_b128 v34, v[44:47] offset:24592
	s_add_i32 s26, s26, 16
	s_waitcnt lgkmcnt(0)
	s_barrier
; DI void scan_item(const Params& p, int item, char* smem) {
;     ...
;   auto gload = [&](int ci) {
; #pragma unroll
;     for (int i = 0; i < 3; i++) {
;       int id = tid + i * 256;
;       int st = id / 48, rem = id % 48, vec = rem >> 3, part = rem & 7;
;       int t = tof(ci * 16 + st);
;       int vi = vec < 3 ? vec : vec + 3 * dir;
;       rg_[i] = *(const u32x4*)(SIb + ((long)t * 9 + vi) * 64 + part * 8);
;     }
;   };
;     ...
;   for (int ci = 0; ci < nch; ci++) {
;     if (ci + 1 < nch) gload(ci + 1);
;     const float* base = sIn + (ci & 1) * 16 * 6 * 64;
;     float ykeep = 0.f;
;     StepIn cur = ldstep(base);
; #pragma unroll
;     for (int st = 0; st < 16; st++) {
;       StepIn nxt = cur;
;       if (st + 1 < 16) nxt = ldstep(base + (st + 1) * 6 * 64);
;       __builtin_amdgcn_sched_barrier(0);
;       f32x2 ra = {cur.r.x, cur.r.y}, rb = {cur.r.z, cur.r.w}, ka = {cur.k.x, cur.k.y}, kb = {cur.k.z, cur.k.w};
;       f32x2 wa = {cur.w.x, cur.w.y}, wb = {cur.w.z, cur.w.w}, da = {cur.d.x, cur.d.y}, db = {cur.d.z, cur.d.w};
;       f32x2 ba = {cur.b.x, cur.b.y}, bb2 = {cur.b.z, cur.b.w};
;       f32x2 pp = Sa * ka + Sb * kb;
;       float sa = allreduce16(pp.x + pp.y);
;       f32x2 vv2 = {cur.v, cur.v};
;       f32x2 sa2 = {sa, sa};
;       Sa = (Sa * wa + vv2 * da) - sa2 * ba;
;       Sb = (Sb * wb + vv2 * db) - sa2 * bb2;
;       f32x2 yy = Sa * ra + Sb * rb;
;       float y = allreduce16(yy.x + yy.y);
;       ykeep = (l16 == st) ? y : ykeep;
;       cur = nxt;
;     }
	ds_read_b128 v[72:75], v49 offset:24832
	ds_read_b32 v88, v50 offset:25088
	ds_read_b128 v[80:83], v49 offset:25600
	ds_read_b128 v[76:79], v49 offset:25344
	ds_read_b128 v[84:87], v49 offset:25856
	ds_read_b128 v[68:71], v49 offset:24576
	ds_read_b128 v[100:103], v49 offset:26368
	ds_read_b32 v116, v50 offset:26624
	ds_read_b128 v[108:111], v49 offset:27136
	ds_read_b128 v[104:107], v49 offset:26880
	ds_read_b128 v[112:115], v49 offset:27392
	ds_read_b128 v[96:99], v49 offset:26112
	s_add_i32 s72, s26, 32
	s_mov_b32 vcc_hi, 0x4c3800
	s_cmp_eq_u32 s72, 0x100
	s_cselect_b32 vcc_lo, vcc_hi, 0xffffb800
	s_cmp_lg_u32 s36, 0
	s_cselect_b32 vcc_lo, 0x4800, vcc_lo
	s_cmp_ge_u32 s72, 0x1100
	s_cselect_b32 vcc_lo, 0, vcc_lo
	s_ashr_i32 vcc_hi, vcc_lo, 31
	v_lshl_add_u64 v[236:237], v[236:237], 0, vcc
	v_lshl_add_u64 v[238:239], v[238:239], 0, vcc
	v_lshl_add_u64 v[240:241], v[240:241], 0, vcc
	global_load_dwordx4 v[0:3], v[236:237], off
	global_load_dwordx4 v[4:7], v[238:239], off
	global_load_dwordx4 v[8:11], v[240:241], off
	s_waitcnt lgkmcnt(6)
	ds_read_b128 v[122:125], v49 offset:27904
	ds_read_b32 v138, v50 offset:28160
	ds_read_b128 v[130:133], v49 offset:28672
	ds_read_b128 v[126:129], v49 offset:28416
	ds_read_b128 v[134:137], v49 offset:28928
	ds_read_b128 v[118:121], v49 offset:27648
	v_pk_mul_f32 v[56:57], v[90:91], v[72:73]
	v_pk_mul_f32 v[60:61], v[88:89], v[80:81] op_sel_hi:[0,1]
	v_pk_fma_f32 v[56:57], v[92:93], v[74:75], v[56:57]
	v_pk_mul_f32 v[62:63], v[88:89], v[82:83] op_sel_hi:[0,1]
	v_add_f32_e32 v58, v56, v57
	v_pk_fma_f32 v[60:61], v[90:91], v[76:77], v[60:61]
	v_pk_fma_f32 v[62:63], v[92:93], v[78:79], v[62:63]
	v_add_f32_dpp v58, v58, v58 quad_perm:[1,0,3,2] row_mask:0xf bank_mask:0xf bound_ctrl:1
	s_nop 1
	v_add_f32_dpp v58, v58, v58 quad_perm:[2,3,0,1] row_mask:0xf bank_mask:0xf bound_ctrl:1
	s_nop 1
	v_add_f32_dpp v58, v58, v58 row_half_mirror row_mask:0xf bank_mask:0xf bound_ctrl:1
	s_nop 1
	v_add_f32_dpp v58, v58, v58 row_mirror row_mask:0xf bank_mask:0xf bound_ctrl:1
	s_nop 0
	v_pk_fma_f32 v[90:91], v[84:85], v[58:59], v[60:61] op_sel_hi:[1,0,1] neg_lo:[1,0,0] neg_hi:[1,0,0]
	v_pk_fma_f32 v[92:93], v[86:87], v[58:59], v[62:63] op_sel_hi:[1,0,1] neg_lo:[1,0,0] neg_hi:[1,0,0]
	s_waitcnt lgkmcnt(6)
	ds_read_b128 v[144:147], v49 offset:29440
	ds_read_b32 v160, v50 offset:29696
	ds_read_b128 v[152:155], v49 offset:30208
	ds_read_b128 v[148:151], v49 offset:29952
	ds_read_b128 v[156:159], v49 offset:30464
	ds_read_b128 v[140:143], v49 offset:29184
	v_pk_mul_f32 v[56:57], v[90:91], v[100:101]
	v_pk_mul_f32 v[64:65], v[70:71], v[92:93]
	v_pk_fma_f32 v[56:57], v[92:93], v[102:103], v[56:57]
	v_pk_fma_f32 v[64:65], v[68:69], v[90:91], v[64:65]
	v_add_f32_e32 v58, v56, v57
	v_add_f32_e32 v66, v64, v65
	v_pk_mul_f32 v[60:61], v[116:117], v[108:109] op_sel_hi:[0,1]
	v_add_f32_dpp v58, v58, v58 quad_perm:[1,0,3,2] row_mask:0xf bank_mask:0xf bound_ctrl:1
	v_add_f32_dpp v66, v66, v66 quad_perm:[1,0,3,2] row_mask:0xf bank_mask:0xf bound_ctrl:1
	v_pk_fma_f32 v[60:61], v[90:91], v[104:105], v[60:61]
	v_add_f32_dpp v58, v58, v58 quad_perm:[2,3,0,1] row_mask:0xf bank_mask:0xf bound_ctrl:1
	v_add_f32_dpp v66, v66, v66 quad_perm:[2,3,0,1] row_mask:0xf bank_mask:0xf bound_ctrl:1
	v_pk_mul_f32 v[62:63], v[116:117], v[110:111] op_sel_hi:[0,1]
	v_add_f32_dpp v58, v58, v58 row_half_mirror row_mask:0xf bank_mask:0xf bound_ctrl:1
	v_add_f32_dpp v66, v66, v66 row_half_mirror row_mask:0xf bank_mask:0xf bound_ctrl:1
	v_pk_fma_f32 v[62:63], v[92:93], v[106:107], v[62:63]
	v_add_f32_dpp v58, v58, v58 row_mirror row_mask:0xf bank_mask:0xf bound_ctrl:1
	v_add_f32_dpp v66, v66, v66 row_mirror row_mask:0xf bank_mask:0xf bound_ctrl:1
	v_pk_fma_f32 v[90:91], v[112:113], v[58:59], v[60:61] op_sel_hi:[1,0,1] neg_lo:[1,0,0] neg_hi:[1,0,0]
	v_pk_fma_f32 v[92:93], v[114:115], v[58:59], v[62:63] op_sel_hi:[1,0,1] neg_lo:[1,0,0] neg_hi:[1,0,0]
	v_cndmask_b32_e64 v67, 0, v66, s[38:39]
	s_waitcnt lgkmcnt(6)
	ds_read_b128 v[72:75], v49 offset:30976
	ds_read_b32 v88, v50 offset:31232
	ds_read_b128 v[80:83], v49 offset:31744
	ds_read_b128 v[76:79], v49 offset:31488
	ds_read_b128 v[84:87], v49 offset:32000
	ds_read_b128 v[68:71], v49 offset:30720
	v_pk_mul_f32 v[56:57], v[90:91], v[122:123]
	v_pk_mul_f32 v[64:65], v[98:99], v[92:93]
	v_pk_fma_f32 v[56:57], v[92:93], v[124:125], v[56:57]
	v_pk_fma_f32 v[64:65], v[96:97], v[90:91], v[64:65]
	v_add_f32_e32 v58, v56, v57
	v_add_f32_e32 v66, v64, v65
	v_pk_mul_f32 v[60:61], v[138:139], v[130:131] op_sel_hi:[0,1]
	v_add_f32_dpp v58, v58, v58 quad_perm:[1,0,3,2] row_mask:0xf bank_mask:0xf bound_ctrl:1
	v_add_f32_dpp v66, v66, v66 quad_perm:[1,0,3,2] row_mask:0xf bank_mask:0xf bound_ctrl:1
	v_pk_fma_f32 v[60:61], v[90:91], v[126:127], v[60:61]
	v_add_f32_dpp v58, v58, v58 quad_perm:[2,3,0,1] row_mask:0xf bank_mask:0xf bound_ctrl:1
	v_add_f32_dpp v66, v66, v66 quad_perm:[2,3,0,1] row_mask:0xf bank_mask:0xf bound_ctrl:1
	v_pk_mul_f32 v[62:63], v[138:139], v[132:133] op_sel_hi:[0,1]
	v_add_f32_dpp v58, v58, v58 row_half_mirror row_mask:0xf bank_mask:0xf bound_ctrl:1
	v_add_f32_dpp v66, v66, v66 row_half_mirror row_mask:0xf bank_mask:0xf bound_ctrl:1
	v_pk_fma_f32 v[62:63], v[92:93], v[128:129], v[62:63]
	v_add_f32_dpp v58, v58, v58 row_mirror row_mask:0xf bank_mask:0xf bound_ctrl:1
	v_add_f32_dpp v66, v66, v66 row_mirror row_mask:0xf bank_mask:0xf bound_ctrl:1
	v_pk_fma_f32 v[90:91], v[134:135], v[58:59], v[60:61] op_sel_hi:[1,0,1] neg_lo:[1,0,0] neg_hi:[1,0,0]
	v_pk_fma_f32 v[92:93], v[136:137], v[58:59], v[62:63] op_sel_hi:[1,0,1] neg_lo:[1,0,0] neg_hi:[1,0,0]
	v_cndmask_b32_e64 v67, v67, v66, s[40:41]
	s_waitcnt lgkmcnt(6)
; DI void scan_item(const Params& p, int item, char* smem) {
;     ...
;     for (int st = 0; st < 16; st++) {
;       StepIn nxt = cur;
;       if (st + 1 < 16) nxt = ldstep(base + (st + 1) * 6 * 64);
;       __builtin_amdgcn_sched_barrier(0);
;       f32x2 ra = {cur.r.x, cur.r.y}, rb = {cur.r.z, cur.r.w}, ka = {cur.k.x, cur.k.y}, kb = {cur.k.z, cur.k.w};
;       f32x2 wa = {cur.w.x, cur.w.y}, wb = {cur.w.z, cur.w.w}, da = {cur.d.x, cur.d.y}, db = {cur.d.z, cur.d.w};
;       f32x2 ba = {cur.b.x, cur.b.y}, bb2 = {cur.b.z, cur.b.w};
;       f32x2 pp = Sa * ka + Sb * kb;
;       float sa = allreduce16(pp.x + pp.y);
;       f32x2 vv2 = {cur.v, cur.v};
;       f32x2 sa2 = {sa, sa};
;       Sa = (Sa * wa + vv2 * da) - sa2 * ba;
;       Sb = (Sb * wb + vv2 * db) - sa2 * bb2;
;       f32x2 yy = Sa * ra + Sb * rb;
;       float y = allreduce16(yy.x + yy.y);
;       ykeep = (l16 == st) ? y : ykeep;
;       cur = nxt;
;     }
	ds_read_b128 v[100:103], v49 offset:32512
	ds_read_b32 v116, v50 offset:32768
	ds_read_b128 v[108:111], v49 offset:33280
	ds_read_b128 v[104:107], v49 offset:33024
	ds_read_b128 v[112:115], v49 offset:33536
	ds_read_b128 v[96:99], v49 offset:32256
	v_pk_mul_f32 v[56:57], v[90:91], v[144:145]
	v_pk_mul_f32 v[64:65], v[120:121], v[92:93]
	v_pk_fma_f32 v[56:57], v[92:93], v[146:147], v[56:57]
	v_pk_fma_f32 v[64:65], v[118:119], v[90:91], v[64:65]
	v_add_f32_e32 v58, v56, v57
	v_add_f32_e32 v66, v64, v65
	v_pk_mul_f32 v[60:61], v[160:161], v[152:153] op_sel_hi:[0,1]
	v_add_f32_dpp v58, v58, v58 quad_perm:[1,0,3,2] row_mask:0xf bank_mask:0xf bound_ctrl:1
	v_add_f32_dpp v66, v66, v66 quad_perm:[1,0,3,2] row_mask:0xf bank_mask:0xf bound_ctrl:1
	v_pk_fma_f32 v[60:61], v[90:91], v[148:149], v[60:61]
	v_add_f32_dpp v58, v58, v58 quad_perm:[2,3,0,1] row_mask:0xf bank_mask:0xf bound_ctrl:1
	v_add_f32_dpp v66, v66, v66 quad_perm:[2,3,0,1] row_mask:0xf bank_mask:0xf bound_ctrl:1
	v_pk_mul_f32 v[62:63], v[160:161], v[154:155] op_sel_hi:[0,1]
	v_add_f32_dpp v58, v58, v58 row_half_mirror row_mask:0xf bank_mask:0xf bound_ctrl:1
	v_add_f32_dpp v66, v66, v66 row_half_mirror row_mask:0xf bank_mask:0xf bound_ctrl:1
	v_pk_fma_f32 v[62:63], v[92:93], v[150:151], v[62:63]
	v_add_f32_dpp v58, v58, v58 row_mirror row_mask:0xf bank_mask:0xf bound_ctrl:1
	v_add_f32_dpp v66, v66, v66 row_mirror row_mask:0xf bank_mask:0xf bound_ctrl:1
	v_pk_fma_f32 v[90:91], v[156:157], v[58:59], v[60:61] op_sel_hi:[1,0,1] neg_lo:[1,0,0] neg_hi:[1,0,0]
	v_pk_fma_f32 v[92:93], v[158:159], v[58:59], v[62:63] op_sel_hi:[1,0,1] neg_lo:[1,0,0] neg_hi:[1,0,0]
	v_cndmask_b32_e64 v67, v67, v66, s[42:43]
	s_waitcnt lgkmcnt(6)
	ds_read_b128 v[122:125], v49 offset:34048
	ds_read_b32 v138, v50 offset:34304
	ds_read_b128 v[130:133], v49 offset:34816
	ds_read_b128 v[126:129], v49 offset:34560
	ds_read_b128 v[134:137], v49 offset:35072
	ds_read_b128 v[118:121], v49 offset:33792
	v_pk_mul_f32 v[56:57], v[90:91], v[72:73]
	v_pk_mul_f32 v[64:65], v[142:143], v[92:93]
	v_pk_fma_f32 v[56:57], v[92:93], v[74:75], v[56:57]
	v_pk_fma_f32 v[64:65], v[140:141], v[90:91], v[64:65]
	v_add_f32_e32 v58, v56, v57
	v_add_f32_e32 v66, v64, v65
	v_pk_mul_f32 v[60:61], v[88:89], v[80:81] op_sel_hi:[0,1]
	v_add_f32_dpp v58, v58, v58 quad_perm:[1,0,3,2] row_mask:0xf bank_mask:0xf bound_ctrl:1
	v_add_f32_dpp v66, v66, v66 quad_perm:[1,0,3,2] row_mask:0xf bank_mask:0xf bound_ctrl:1
	v_pk_fma_f32 v[60:61], v[90:91], v[76:77], v[60:61]
	v_add_f32_dpp v58, v58, v58 quad_perm:[2,3,0,1] row_mask:0xf bank_mask:0xf bound_ctrl:1
	v_add_f32_dpp v66, v66, v66 quad_perm:[2,3,0,1] row_mask:0xf bank_mask:0xf bound_ctrl:1
	v_pk_mul_f32 v[62:63], v[88:89], v[82:83] op_sel_hi:[0,1]
	v_add_f32_dpp v58, v58, v58 row_half_mirror row_mask:0xf bank_mask:0xf bound_ctrl:1
	v_add_f32_dpp v66, v66, v66 row_half_mirror row_mask:0xf bank_mask:0xf bound_ctrl:1
	v_pk_fma_f32 v[62:63], v[92:93], v[78:79], v[62:63]
	v_add_f32_dpp v58, v58, v58 row_mirror row_mask:0xf bank_mask:0xf bound_ctrl:1
	v_add_f32_dpp v66, v66, v66 row_mirror row_mask:0xf bank_mask:0xf bound_ctrl:1
	v_pk_fma_f32 v[90:91], v[84:85], v[58:59], v[60:61] op_sel_hi:[1,0,1] neg_lo:[1,0,0] neg_hi:[1,0,0]
	v_pk_fma_f32 v[92:93], v[86:87], v[58:59], v[62:63] op_sel_hi:[1,0,1] neg_lo:[1,0,0] neg_hi:[1,0,0]
	v_cndmask_b32_e64 v67, v67, v66, s[44:45]
	s_waitcnt lgkmcnt(6)
	ds_read_b128 v[144:147], v49 offset:35584
	ds_read_b32 v160, v50 offset:35840
	ds_read_b128 v[152:155], v49 offset:36352
	ds_read_b128 v[148:151], v49 offset:36096
	ds_read_b128 v[156:159], v49 offset:36608
	ds_read_b128 v[140:143], v49 offset:35328
	v_pk_mul_f32 v[56:57], v[90:91], v[100:101]
	v_pk_mul_f32 v[64:65], v[70:71], v[92:93]
	v_pk_fma_f32 v[56:57], v[92:93], v[102:103], v[56:57]
	v_pk_fma_f32 v[64:65], v[68:69], v[90:91], v[64:65]
	v_add_f32_e32 v58, v56, v57
	v_add_f32_e32 v66, v64, v65
	v_pk_mul_f32 v[60:61], v[116:117], v[108:109] op_sel_hi:[0,1]
	v_add_f32_dpp v58, v58, v58 quad_perm:[1,0,3,2] row_mask:0xf bank_mask:0xf bound_ctrl:1
	v_add_f32_dpp v66, v66, v66 quad_perm:[1,0,3,2] row_mask:0xf bank_mask:0xf bound_ctrl:1
	v_pk_fma_f32 v[60:61], v[90:91], v[104:105], v[60:61]
	v_add_f32_dpp v58, v58, v58 quad_perm:[2,3,0,1] row_mask:0xf bank_mask:0xf bound_ctrl:1
	v_add_f32_dpp v66, v66, v66 quad_perm:[2,3,0,1] row_mask:0xf bank_mask:0xf bound_ctrl:1
	v_pk_mul_f32 v[62:63], v[116:117], v[110:111] op_sel_hi:[0,1]
	v_add_f32_dpp v58, v58, v58 row_half_mirror row_mask:0xf bank_mask:0xf bound_ctrl:1
	v_add_f32_dpp v66, v66, v66 row_half_mirror row_mask:0xf bank_mask:0xf bound_ctrl:1
	v_pk_fma_f32 v[62:63], v[92:93], v[106:107], v[62:63]
	v_add_f32_dpp v58, v58, v58 row_mirror row_mask:0xf bank_mask:0xf bound_ctrl:1
	v_add_f32_dpp v66, v66, v66 row_mirror row_mask:0xf bank_mask:0xf bound_ctrl:1
	v_pk_fma_f32 v[90:91], v[112:113], v[58:59], v[60:61] op_sel_hi:[1,0,1] neg_lo:[1,0,0] neg_hi:[1,0,0]
	v_pk_fma_f32 v[92:93], v[114:115], v[58:59], v[62:63] op_sel_hi:[1,0,1] neg_lo:[1,0,0] neg_hi:[1,0,0]
	v_cndmask_b32_e64 v67, v67, v66, s[46:47]
	s_waitcnt lgkmcnt(6)
; DI void scan_item(const Params& p, int item, char* smem) {
;     ...
;     for (int st = 0; st < 16; st++) {
;       StepIn nxt = cur;
;       if (st + 1 < 16) nxt = ldstep(base + (st + 1) * 6 * 64);
;       __builtin_amdgcn_sched_barrier(0);
;       f32x2 ra = {cur.r.x, cur.r.y}, rb = {cur.r.z, cur.r.w}, ka = {cur.k.x, cur.k.y}, kb = {cur.k.z, cur.k.w};
;       f32x2 wa = {cur.w.x, cur.w.y}, wb = {cur.w.z, cur.w.w}, da = {cur.d.x, cur.d.y}, db = {cur.d.z, cur.d.w};
;       f32x2 ba = {cur.b.x, cur.b.y}, bb2 = {cur.b.z, cur.b.w};
;       f32x2 pp = Sa * ka + Sb * kb;
;       float sa = allreduce16(pp.x + pp.y);
;       f32x2 vv2 = {cur.v, cur.v};
;       f32x2 sa2 = {sa, sa};
;       Sa = (Sa * wa + vv2 * da) - sa2 * ba;
;       Sb = (Sb * wb + vv2 * db) - sa2 * bb2;
;       f32x2 yy = Sa * ra + Sb * rb;
;       float y = allreduce16(yy.x + yy.y);
;       ykeep = (l16 == st) ? y : ykeep;
;       cur = nxt;
;     }
	ds_read_b128 v[72:75], v49 offset:37120
	ds_read_b32 v88, v50 offset:37376
	ds_read_b128 v[80:83], v49 offset:37888
	ds_read_b128 v[76:79], v49 offset:37632
	ds_read_b128 v[84:87], v49 offset:38144
	ds_read_b128 v[68:71], v49 offset:36864
	v_pk_mul_f32 v[56:57], v[90:91], v[122:123]
	v_pk_mul_f32 v[64:65], v[98:99], v[92:93]
	v_pk_fma_f32 v[56:57], v[92:93], v[124:125], v[56:57]
	v_pk_fma_f32 v[64:65], v[96:97], v[90:91], v[64:65]
	v_add_f32_e32 v58, v56, v57
	v_add_f32_e32 v66, v64, v65
	v_pk_mul_f32 v[60:61], v[138:139], v[130:131] op_sel_hi:[0,1]
	v_add_f32_dpp v58, v58, v58 quad_perm:[1,0,3,2] row_mask:0xf bank_mask:0xf bound_ctrl:1
	v_add_f32_dpp v66, v66, v66 quad_perm:[1,0,3,2] row_mask:0xf bank_mask:0xf bound_ctrl:1
	v_pk_fma_f32 v[60:61], v[90:91], v[126:127], v[60:61]
	v_add_f32_dpp v58, v58, v58 quad_perm:[2,3,0,1] row_mask:0xf bank_mask:0xf bound_ctrl:1
	v_add_f32_dpp v66, v66, v66 quad_perm:[2,3,0,1] row_mask:0xf bank_mask:0xf bound_ctrl:1
	v_pk_mul_f32 v[62:63], v[138:139], v[132:133] op_sel_hi:[0,1]
	v_add_f32_dpp v58, v58, v58 row_half_mirror row_mask:0xf bank_mask:0xf bound_ctrl:1
	v_add_f32_dpp v66, v66, v66 row_half_mirror row_mask:0xf bank_mask:0xf bound_ctrl:1
	v_pk_fma_f32 v[62:63], v[92:93], v[128:129], v[62:63]
	v_add_f32_dpp v58, v58, v58 row_mirror row_mask:0xf bank_mask:0xf bound_ctrl:1
	v_add_f32_dpp v66, v66, v66 row_mirror row_mask:0xf bank_mask:0xf bound_ctrl:1
	v_pk_fma_f32 v[90:91], v[134:135], v[58:59], v[60:61] op_sel_hi:[1,0,1] neg_lo:[1,0,0] neg_hi:[1,0,0]
	v_pk_fma_f32 v[92:93], v[136:137], v[58:59], v[62:63] op_sel_hi:[1,0,1] neg_lo:[1,0,0] neg_hi:[1,0,0]
	v_cndmask_b32_e64 v67, v67, v66, s[48:49]
	s_waitcnt lgkmcnt(6)
	ds_read_b128 v[100:103], v49 offset:38656
	ds_read_b32 v116, v50 offset:38912
	ds_read_b128 v[108:111], v49 offset:39424
	ds_read_b128 v[104:107], v49 offset:39168
	ds_read_b128 v[112:115], v49 offset:39680
	ds_read_b128 v[96:99], v49 offset:38400
	v_pk_mul_f32 v[56:57], v[90:91], v[144:145]
	v_pk_mul_f32 v[64:65], v[120:121], v[92:93]
	v_pk_fma_f32 v[56:57], v[92:93], v[146:147], v[56:57]
	v_pk_fma_f32 v[64:65], v[118:119], v[90:91], v[64:65]
	v_add_f32_e32 v58, v56, v57
	v_add_f32_e32 v66, v64, v65
	v_pk_mul_f32 v[60:61], v[160:161], v[152:153] op_sel_hi:[0,1]
	v_add_f32_dpp v58, v58, v58 quad_perm:[1,0,3,2] row_mask:0xf bank_mask:0xf bound_ctrl:1
	v_add_f32_dpp v66, v66, v66 quad_perm:[1,0,3,2] row_mask:0xf bank_mask:0xf bound_ctrl:1
	v_pk_fma_f32 v[60:61], v[90:91], v[148:149], v[60:61]
	v_add_f32_dpp v58, v58, v58 quad_perm:[2,3,0,1] row_mask:0xf bank_mask:0xf bound_ctrl:1
	v_add_f32_dpp v66, v66, v66 quad_perm:[2,3,0,1] row_mask:0xf bank_mask:0xf bound_ctrl:1
	v_pk_mul_f32 v[62:63], v[160:161], v[154:155] op_sel_hi:[0,1]
	v_add_f32_dpp v58, v58, v58 row_half_mirror row_mask:0xf bank_mask:0xf bound_ctrl:1
	v_add_f32_dpp v66, v66, v66 row_half_mirror row_mask:0xf bank_mask:0xf bound_ctrl:1
	v_pk_fma_f32 v[62:63], v[92:93], v[150:151], v[62:63]
	v_add_f32_dpp v58, v58, v58 row_mirror row_mask:0xf bank_mask:0xf bound_ctrl:1
	v_add_f32_dpp v66, v66, v66 row_mirror row_mask:0xf bank_mask:0xf bound_ctrl:1
	v_pk_fma_f32 v[90:91], v[156:157], v[58:59], v[60:61] op_sel_hi:[1,0,1] neg_lo:[1,0,0] neg_hi:[1,0,0]
	v_pk_fma_f32 v[92:93], v[158:159], v[58:59], v[62:63] op_sel_hi:[1,0,1] neg_lo:[1,0,0] neg_hi:[1,0,0]
	v_cndmask_b32_e64 v67, v67, v66, s[50:51]
	s_waitcnt lgkmcnt(6)
	ds_read_b128 v[122:125], v49 offset:40192
	ds_read_b32 v138, v50 offset:40448
	ds_read_b128 v[130:133], v49 offset:40960
	ds_read_b128 v[126:129], v49 offset:40704
	ds_read_b128 v[134:137], v49 offset:41216
	ds_read_b128 v[118:121], v49 offset:39936
	v_pk_mul_f32 v[56:57], v[90:91], v[72:73]
	v_pk_mul_f32 v[64:65], v[142:143], v[92:93]
	v_pk_fma_f32 v[56:57], v[92:93], v[74:75], v[56:57]
	v_pk_fma_f32 v[64:65], v[140:141], v[90:91], v[64:65]
	v_add_f32_e32 v58, v56, v57
	v_add_f32_e32 v66, v64, v65
	v_pk_mul_f32 v[60:61], v[88:89], v[80:81] op_sel_hi:[0,1]
	v_add_f32_dpp v58, v58, v58 quad_perm:[1,0,3,2] row_mask:0xf bank_mask:0xf bound_ctrl:1
	v_add_f32_dpp v66, v66, v66 quad_perm:[1,0,3,2] row_mask:0xf bank_mask:0xf bound_ctrl:1
	v_pk_fma_f32 v[60:61], v[90:91], v[76:77], v[60:61]
	v_add_f32_dpp v58, v58, v58 quad_perm:[2,3,0,1] row_mask:0xf bank_mask:0xf bound_ctrl:1
	v_add_f32_dpp v66, v66, v66 quad_perm:[2,3,0,1] row_mask:0xf bank_mask:0xf bound_ctrl:1
	v_pk_mul_f32 v[62:63], v[88:89], v[82:83] op_sel_hi:[0,1]
	v_add_f32_dpp v58, v58, v58 row_half_mirror row_mask:0xf bank_mask:0xf bound_ctrl:1
	v_add_f32_dpp v66, v66, v66 row_half_mirror row_mask:0xf bank_mask:0xf bound_ctrl:1
	v_pk_fma_f32 v[62:63], v[92:93], v[78:79], v[62:63]
	v_add_f32_dpp v58, v58, v58 row_mirror row_mask:0xf bank_mask:0xf bound_ctrl:1
	v_add_f32_dpp v66, v66, v66 row_mirror row_mask:0xf bank_mask:0xf bound_ctrl:1
	v_pk_fma_f32 v[90:91], v[84:85], v[58:59], v[60:61] op_sel_hi:[1,0,1] neg_lo:[1,0,0] neg_hi:[1,0,0]
	v_pk_fma_f32 v[92:93], v[86:87], v[58:59], v[62:63] op_sel_hi:[1,0,1] neg_lo:[1,0,0] neg_hi:[1,0,0]
	v_cndmask_b32_e64 v67, v67, v66, s[52:53]
	s_waitcnt lgkmcnt(6)
; DI void scan_item(const Params& p, int item, char* smem) {
;     ...
;     for (int st = 0; st < 16; st++) {
;       StepIn nxt = cur;
;       if (st + 1 < 16) nxt = ldstep(base + (st + 1) * 6 * 64);
;       __builtin_amdgcn_sched_barrier(0);
;       f32x2 ra = {cur.r.x, cur.r.y}, rb = {cur.r.z, cur.r.w}, ka = {cur.k.x, cur.k.y}, kb = {cur.k.z, cur.k.w};
;       f32x2 wa = {cur.w.x, cur.w.y}, wb = {cur.w.z, cur.w.w}, da = {cur.d.x, cur.d.y}, db = {cur.d.z, cur.d.w};
;       f32x2 ba = {cur.b.x, cur.b.y}, bb2 = {cur.b.z, cur.b.w};
;       f32x2 pp = Sa * ka + Sb * kb;
;       float sa = allreduce16(pp.x + pp.y);
;       f32x2 vv2 = {cur.v, cur.v};
;       f32x2 sa2 = {sa, sa};
;       Sa = (Sa * wa + vv2 * da) - sa2 * ba;
;       Sb = (Sb * wb + vv2 * db) - sa2 * bb2;
;       f32x2 yy = Sa * ra + Sb * rb;
;       float y = allreduce16(yy.x + yy.y);
;       ykeep = (l16 == st) ? y : ykeep;
;       cur = nxt;
;     }
	ds_read_b128 v[144:147], v49 offset:41728
	ds_read_b32 v160, v50 offset:41984
	ds_read_b128 v[152:155], v49 offset:42496
	ds_read_b128 v[148:151], v49 offset:42240
	ds_read_b128 v[156:159], v49 offset:42752
	ds_read_b128 v[140:143], v49 offset:41472
	v_pk_mul_f32 v[56:57], v[90:91], v[100:101]
	v_pk_mul_f32 v[64:65], v[70:71], v[92:93]
	v_pk_fma_f32 v[56:57], v[92:93], v[102:103], v[56:57]
	v_pk_fma_f32 v[64:65], v[68:69], v[90:91], v[64:65]
	v_add_f32_e32 v58, v56, v57
	v_add_f32_e32 v66, v64, v65
	v_pk_mul_f32 v[60:61], v[116:117], v[108:109] op_sel_hi:[0,1]
	v_add_f32_dpp v58, v58, v58 quad_perm:[1,0,3,2] row_mask:0xf bank_mask:0xf bound_ctrl:1
	v_add_f32_dpp v66, v66, v66 quad_perm:[1,0,3,2] row_mask:0xf bank_mask:0xf bound_ctrl:1
	v_pk_fma_f32 v[60:61], v[90:91], v[104:105], v[60:61]
	v_add_f32_dpp v58, v58, v58 quad_perm:[2,3,0,1] row_mask:0xf bank_mask:0xf bound_ctrl:1
	v_add_f32_dpp v66, v66, v66 quad_perm:[2,3,0,1] row_mask:0xf bank_mask:0xf bound_ctrl:1
	v_pk_mul_f32 v[62:63], v[116:117], v[110:111] op_sel_hi:[0,1]
	v_add_f32_dpp v58, v58, v58 row_half_mirror row_mask:0xf bank_mask:0xf bound_ctrl:1
	v_add_f32_dpp v66, v66, v66 row_half_mirror row_mask:0xf bank_mask:0xf bound_ctrl:1
	v_pk_fma_f32 v[62:63], v[92:93], v[106:107], v[62:63]
	v_add_f32_dpp v58, v58, v58 row_mirror row_mask:0xf bank_mask:0xf bound_ctrl:1
	v_add_f32_dpp v66, v66, v66 row_mirror row_mask:0xf bank_mask:0xf bound_ctrl:1
	v_pk_fma_f32 v[90:91], v[112:113], v[58:59], v[60:61] op_sel_hi:[1,0,1] neg_lo:[1,0,0] neg_hi:[1,0,0]
	v_pk_fma_f32 v[92:93], v[114:115], v[58:59], v[62:63] op_sel_hi:[1,0,1] neg_lo:[1,0,0] neg_hi:[1,0,0]
	v_cndmask_b32_e64 v67, v67, v66, s[54:55]
	s_waitcnt lgkmcnt(6)
	ds_read_b128 v[72:75], v49 offset:43264
	ds_read_b32 v88, v50 offset:43520
	ds_read_b128 v[80:83], v49 offset:44032
	ds_read_b128 v[76:79], v49 offset:43776
	ds_read_b128 v[84:87], v49 offset:44288
	ds_read_b128 v[68:71], v49 offset:43008
	v_pk_mul_f32 v[56:57], v[90:91], v[122:123]
	v_pk_mul_f32 v[64:65], v[98:99], v[92:93]
	v_pk_fma_f32 v[56:57], v[92:93], v[124:125], v[56:57]
	v_pk_fma_f32 v[64:65], v[96:97], v[90:91], v[64:65]
	v_add_f32_e32 v58, v56, v57
	v_add_f32_e32 v66, v64, v65
	v_pk_mul_f32 v[60:61], v[138:139], v[130:131] op_sel_hi:[0,1]
	v_add_f32_dpp v58, v58, v58 quad_perm:[1,0,3,2] row_mask:0xf bank_mask:0xf bound_ctrl:1
	v_add_f32_dpp v66, v66, v66 quad_perm:[1,0,3,2] row_mask:0xf bank_mask:0xf bound_ctrl:1
	v_pk_fma_f32 v[60:61], v[90:91], v[126:127], v[60:61]
	v_add_f32_dpp v58, v58, v58 quad_perm:[2,3,0,1] row_mask:0xf bank_mask:0xf bound_ctrl:1
	v_add_f32_dpp v66, v66, v66 quad_perm:[2,3,0,1] row_mask:0xf bank_mask:0xf bound_ctrl:1
	v_pk_mul_f32 v[62:63], v[138:139], v[132:133] op_sel_hi:[0,1]
	v_add_f32_dpp v58, v58, v58 row_half_mirror row_mask:0xf bank_mask:0xf bound_ctrl:1
	v_add_f32_dpp v66, v66, v66 row_half_mirror row_mask:0xf bank_mask:0xf bound_ctrl:1
	v_pk_fma_f32 v[62:63], v[92:93], v[128:129], v[62:63]
	v_add_f32_dpp v58, v58, v58 row_mirror row_mask:0xf bank_mask:0xf bound_ctrl:1
	v_add_f32_dpp v66, v66, v66 row_mirror row_mask:0xf bank_mask:0xf bound_ctrl:1
	v_pk_fma_f32 v[90:91], v[134:135], v[58:59], v[60:61] op_sel_hi:[1,0,1] neg_lo:[1,0,0] neg_hi:[1,0,0]
	v_pk_fma_f32 v[92:93], v[136:137], v[58:59], v[62:63] op_sel_hi:[1,0,1] neg_lo:[1,0,0] neg_hi:[1,0,0]
	v_cndmask_b32_e64 v67, v67, v66, s[56:57]
	s_waitcnt lgkmcnt(6)
	ds_read_b128 v[100:103], v49 offset:44800
	ds_read_b32 v116, v50 offset:45056
	ds_read_b128 v[108:111], v49 offset:45568
	ds_read_b128 v[104:107], v49 offset:45312
	ds_read_b128 v[112:115], v49 offset:45824
	ds_read_b128 v[96:99], v49 offset:44544
	v_pk_mul_f32 v[56:57], v[90:91], v[144:145]
	v_pk_mul_f32 v[64:65], v[120:121], v[92:93]
	v_pk_fma_f32 v[56:57], v[92:93], v[146:147], v[56:57]
	v_pk_fma_f32 v[64:65], v[118:119], v[90:91], v[64:65]
	v_add_f32_e32 v58, v56, v57
	v_add_f32_e32 v66, v64, v65
	v_pk_mul_f32 v[60:61], v[160:161], v[152:153] op_sel_hi:[0,1]
	v_add_f32_dpp v58, v58, v58 quad_perm:[1,0,3,2] row_mask:0xf bank_mask:0xf bound_ctrl:1
	v_add_f32_dpp v66, v66, v66 quad_perm:[1,0,3,2] row_mask:0xf bank_mask:0xf bound_ctrl:1
	v_pk_fma_f32 v[60:61], v[90:91], v[148:149], v[60:61]
	v_add_f32_dpp v58, v58, v58 quad_perm:[2,3,0,1] row_mask:0xf bank_mask:0xf bound_ctrl:1
	v_add_f32_dpp v66, v66, v66 quad_perm:[2,3,0,1] row_mask:0xf bank_mask:0xf bound_ctrl:1
	v_pk_mul_f32 v[62:63], v[160:161], v[154:155] op_sel_hi:[0,1]
	v_add_f32_dpp v58, v58, v58 row_half_mirror row_mask:0xf bank_mask:0xf bound_ctrl:1
	v_add_f32_dpp v66, v66, v66 row_half_mirror row_mask:0xf bank_mask:0xf bound_ctrl:1
	v_pk_fma_f32 v[62:63], v[92:93], v[150:151], v[62:63]
	v_add_f32_dpp v58, v58, v58 row_mirror row_mask:0xf bank_mask:0xf bound_ctrl:1
	v_add_f32_dpp v66, v66, v66 row_mirror row_mask:0xf bank_mask:0xf bound_ctrl:1
	v_pk_fma_f32 v[90:91], v[156:157], v[58:59], v[60:61] op_sel_hi:[1,0,1] neg_lo:[1,0,0] neg_hi:[1,0,0]
	v_pk_fma_f32 v[92:93], v[158:159], v[58:59], v[62:63] op_sel_hi:[1,0,1] neg_lo:[1,0,0] neg_hi:[1,0,0]
	v_cndmask_b32_e64 v67, v67, v66, s[58:59]
	s_waitcnt lgkmcnt(6)
; DI void scan_item(const Params& p, int item, char* smem) {
;     ...
;     for (int st = 0; st < 16; st++) {
;       StepIn nxt = cur;
;       if (st + 1 < 16) nxt = ldstep(base + (st + 1) * 6 * 64);
;       __builtin_amdgcn_sched_barrier(0);
;       f32x2 ra = {cur.r.x, cur.r.y}, rb = {cur.r.z, cur.r.w}, ka = {cur.k.x, cur.k.y}, kb = {cur.k.z, cur.k.w};
;       f32x2 wa = {cur.w.x, cur.w.y}, wb = {cur.w.z, cur.w.w}, da = {cur.d.x, cur.d.y}, db = {cur.d.z, cur.d.w};
;       f32x2 ba = {cur.b.x, cur.b.y}, bb2 = {cur.b.z, cur.b.w};
;       f32x2 pp = Sa * ka + Sb * kb;
;       float sa = allreduce16(pp.x + pp.y);
;       f32x2 vv2 = {cur.v, cur.v};
;       f32x2 sa2 = {sa, sa};
;       Sa = (Sa * wa + vv2 * da) - sa2 * ba;
;       Sb = (Sb * wb + vv2 * db) - sa2 * bb2;
;       f32x2 yy = Sa * ra + Sb * rb;
;       float y = allreduce16(yy.x + yy.y);
;       ykeep = (l16 == st) ? y : ykeep;
;       cur = nxt;
;     }
	ds_read_b128 v[122:125], v49 offset:46336
	ds_read_b32 v138, v50 offset:46592
	ds_read_b128 v[130:133], v49 offset:47104
	ds_read_b128 v[126:129], v49 offset:46848
	ds_read_b128 v[134:137], v49 offset:47360
	ds_read_b128 v[118:121], v49 offset:46080
	v_pk_mul_f32 v[56:57], v[90:91], v[72:73]
	v_pk_mul_f32 v[64:65], v[142:143], v[92:93]
	v_pk_fma_f32 v[56:57], v[92:93], v[74:75], v[56:57]
	v_pk_fma_f32 v[64:65], v[140:141], v[90:91], v[64:65]
	v_add_f32_e32 v58, v56, v57
	v_add_f32_e32 v66, v64, v65
	v_pk_mul_f32 v[60:61], v[88:89], v[80:81] op_sel_hi:[0,1]
	v_add_f32_dpp v58, v58, v58 quad_perm:[1,0,3,2] row_mask:0xf bank_mask:0xf bound_ctrl:1
	v_add_f32_dpp v66, v66, v66 quad_perm:[1,0,3,2] row_mask:0xf bank_mask:0xf bound_ctrl:1
	v_pk_fma_f32 v[60:61], v[90:91], v[76:77], v[60:61]
	v_add_f32_dpp v58, v58, v58 quad_perm:[2,3,0,1] row_mask:0xf bank_mask:0xf bound_ctrl:1
	v_add_f32_dpp v66, v66, v66 quad_perm:[2,3,0,1] row_mask:0xf bank_mask:0xf bound_ctrl:1
	v_pk_mul_f32 v[62:63], v[88:89], v[82:83] op_sel_hi:[0,1]
	v_add_f32_dpp v58, v58, v58 row_half_mirror row_mask:0xf bank_mask:0xf bound_ctrl:1
	v_add_f32_dpp v66, v66, v66 row_half_mirror row_mask:0xf bank_mask:0xf bound_ctrl:1
	v_pk_fma_f32 v[62:63], v[92:93], v[78:79], v[62:63]
	v_add_f32_dpp v58, v58, v58 row_mirror row_mask:0xf bank_mask:0xf bound_ctrl:1
	v_add_f32_dpp v66, v66, v66 row_mirror row_mask:0xf bank_mask:0xf bound_ctrl:1
	v_pk_fma_f32 v[90:91], v[84:85], v[58:59], v[60:61] op_sel_hi:[1,0,1] neg_lo:[1,0,0] neg_hi:[1,0,0]
	v_pk_fma_f32 v[92:93], v[86:87], v[58:59], v[62:63] op_sel_hi:[1,0,1] neg_lo:[1,0,0] neg_hi:[1,0,0]
	v_cndmask_b32_e64 v67, v67, v66, s[60:61]
	s_waitcnt lgkmcnt(6)
	ds_read_b128 v[144:147], v49 offset:47872
	ds_read_b32 v160, v50 offset:48128
	ds_read_b128 v[152:155], v49 offset:48640
	ds_read_b128 v[148:151], v49 offset:48384
	ds_read_b128 v[156:159], v49 offset:48896
	ds_read_b128 v[140:143], v49 offset:47616
	v_pk_mul_f32 v[56:57], v[90:91], v[100:101]
	v_pk_mul_f32 v[64:65], v[70:71], v[92:93]
	v_pk_fma_f32 v[56:57], v[92:93], v[102:103], v[56:57]
	v_pk_fma_f32 v[64:65], v[68:69], v[90:91], v[64:65]
	v_add_f32_e32 v58, v56, v57
	v_add_f32_e32 v66, v64, v65
	v_pk_mul_f32 v[60:61], v[116:117], v[108:109] op_sel_hi:[0,1]
	v_add_f32_dpp v58, v58, v58 quad_perm:[1,0,3,2] row_mask:0xf bank_mask:0xf bound_ctrl:1
	v_add_f32_dpp v66, v66, v66 quad_perm:[1,0,3,2] row_mask:0xf bank_mask:0xf bound_ctrl:1
	v_pk_fma_f32 v[60:61], v[90:91], v[104:105], v[60:61]
	v_add_f32_dpp v58, v58, v58 quad_perm:[2,3,0,1] row_mask:0xf bank_mask:0xf bound_ctrl:1
	v_add_f32_dpp v66, v66, v66 quad_perm:[2,3,0,1] row_mask:0xf bank_mask:0xf bound_ctrl:1
	v_pk_mul_f32 v[62:63], v[116:117], v[110:111] op_sel_hi:[0,1]
	v_add_f32_dpp v58, v58, v58 row_half_mirror row_mask:0xf bank_mask:0xf bound_ctrl:1
	v_add_f32_dpp v66, v66, v66 row_half_mirror row_mask:0xf bank_mask:0xf bound_ctrl:1
	v_pk_fma_f32 v[62:63], v[92:93], v[106:107], v[62:63]
	v_add_f32_dpp v58, v58, v58 row_mirror row_mask:0xf bank_mask:0xf bound_ctrl:1
	v_add_f32_dpp v66, v66, v66 row_mirror row_mask:0xf bank_mask:0xf bound_ctrl:1
	v_pk_fma_f32 v[90:91], v[112:113], v[58:59], v[60:61] op_sel_hi:[1,0,1] neg_lo:[1,0,0] neg_hi:[1,0,0]
	v_pk_fma_f32 v[92:93], v[114:115], v[58:59], v[62:63] op_sel_hi:[1,0,1] neg_lo:[1,0,0] neg_hi:[1,0,0]
	v_cndmask_b32_e64 v67, v67, v66, s[62:63]
	s_waitcnt lgkmcnt(6)
	v_pk_mul_f32 v[56:57], v[90:91], v[122:123]
	v_pk_mul_f32 v[64:65], v[98:99], v[92:93]
	v_pk_fma_f32 v[56:57], v[92:93], v[124:125], v[56:57]
	v_pk_fma_f32 v[64:65], v[96:97], v[90:91], v[64:65]
	v_add_f32_e32 v58, v56, v57
	v_add_f32_e32 v66, v64, v65
	v_pk_mul_f32 v[60:61], v[138:139], v[130:131] op_sel_hi:[0,1]
	v_add_f32_dpp v58, v58, v58 quad_perm:[1,0,3,2] row_mask:0xf bank_mask:0xf bound_ctrl:1
	v_add_f32_dpp v66, v66, v66 quad_perm:[1,0,3,2] row_mask:0xf bank_mask:0xf bound_ctrl:1
	v_pk_fma_f32 v[60:61], v[90:91], v[126:127], v[60:61]
	v_add_f32_dpp v58, v58, v58 quad_perm:[2,3,0,1] row_mask:0xf bank_mask:0xf bound_ctrl:1
	v_add_f32_dpp v66, v66, v66 quad_perm:[2,3,0,1] row_mask:0xf bank_mask:0xf bound_ctrl:1
	v_pk_mul_f32 v[62:63], v[138:139], v[132:133] op_sel_hi:[0,1]
	v_add_f32_dpp v58, v58, v58 row_half_mirror row_mask:0xf bank_mask:0xf bound_ctrl:1
	v_add_f32_dpp v66, v66, v66 row_half_mirror row_mask:0xf bank_mask:0xf bound_ctrl:1
	v_pk_fma_f32 v[62:63], v[92:93], v[128:129], v[62:63]
	v_add_f32_dpp v58, v58, v58 row_mirror row_mask:0xf bank_mask:0xf bound_ctrl:1
	v_add_f32_dpp v66, v66, v66 row_mirror row_mask:0xf bank_mask:0xf bound_ctrl:1
	v_pk_fma_f32 v[90:91], v[134:135], v[58:59], v[60:61] op_sel_hi:[1,0,1] neg_lo:[1,0,0] neg_hi:[1,0,0]
	v_pk_fma_f32 v[92:93], v[136:137], v[58:59], v[62:63] op_sel_hi:[1,0,1] neg_lo:[1,0,0] neg_hi:[1,0,0]
	v_cndmask_b32_e64 v67, v67, v66, s[64:65]
	s_waitcnt lgkmcnt(0)
; DI void scan_item(const Params& p, int item, char* smem) {
;     ...
;   auto lstore = [&](int buf) {
; #pragma unroll
;     for (int i = 0; i < 3; i++) {
;       int id = tid + i * 256;
;       int st = id / 48, rem = id % 48, vec = rem >> 3, part = rem & 7;
;       h8 hv = __builtin_bit_cast(h8, rg_[i]);
;       f8 fv = __builtin_convertvector(hv, f8);
;       float* d = sIn + ((buf * 16 + st) * 6 + vec) * 64 + part * 8;
;       *(f32x4v*)d = f32x4v{fv[0], fv[1], fv[2], fv[3]};
;       *(f32x4v*)(d + 4) = f32x4v{fv[4], fv[5], fv[6], fv[7]};
;     }
;   };
;     ...
;     for (int st = 0; st < 16; st++) {
;       StepIn nxt = cur;
;       if (st + 1 < 16) nxt = ldstep(base + (st + 1) * 6 * 64);
;       __builtin_amdgcn_sched_barrier(0);
;       f32x2 ra = {cur.r.x, cur.r.y}, rb = {cur.r.z, cur.r.w}, ka = {cur.k.x, cur.k.y}, kb = {cur.k.z, cur.k.w};
;       f32x2 wa = {cur.w.x, cur.w.y}, wb = {cur.w.z, cur.w.w}, da = {cur.d.x, cur.d.y}, db = {cur.d.z, cur.d.w};
;       f32x2 ba = {cur.b.x, cur.b.y}, bb2 = {cur.b.z, cur.b.w};
;       f32x2 pp = Sa * ka + Sb * kb;
;       float sa = allreduce16(pp.x + pp.y);
;       f32x2 vv2 = {cur.v, cur.v};
;       f32x2 sa2 = {sa, sa};
;       Sa = (Sa * wa + vv2 * da) - sa2 * ba;
;       Sb = (Sb * wb + vv2 * db) - sa2 * bb2;
;       f32x2 yy = Sa * ra + Sb * rb;
;       float y = allreduce16(yy.x + yy.y);
;       ykeep = (l16 == st) ? y : ykeep;
;       cur = nxt;
;     }
;     { _Float16 yh = (_Float16)ykeep; yb[(long)tof(ci * 16 + l16) * 256 + rowl] = __builtin_bit_cast(u16, yh); }
;     if (ci + 1 < nch) lstore((ci + 1) & 1);
;     __syncthreads();
;   }
	v_pk_mul_f32 v[56:57], v[90:91], v[144:145]
	v_pk_mul_f32 v[64:65], v[120:121], v[92:93]
	v_pk_fma_f32 v[56:57], v[92:93], v[146:147], v[56:57]
	v_pk_fma_f32 v[64:65], v[118:119], v[90:91], v[64:65]
	v_add_f32_e32 v58, v56, v57
	v_add_f32_e32 v66, v64, v65
	v_pk_mul_f32 v[60:61], v[160:161], v[152:153] op_sel_hi:[0,1]
	v_add_f32_dpp v58, v58, v58 quad_perm:[1,0,3,2] row_mask:0xf bank_mask:0xf bound_ctrl:1
	v_add_f32_dpp v66, v66, v66 quad_perm:[1,0,3,2] row_mask:0xf bank_mask:0xf bound_ctrl:1
	v_pk_fma_f32 v[60:61], v[90:91], v[148:149], v[60:61]
	v_add_f32_dpp v58, v58, v58 quad_perm:[2,3,0,1] row_mask:0xf bank_mask:0xf bound_ctrl:1
	v_add_f32_dpp v66, v66, v66 quad_perm:[2,3,0,1] row_mask:0xf bank_mask:0xf bound_ctrl:1
	v_pk_mul_f32 v[62:63], v[160:161], v[154:155] op_sel_hi:[0,1]
	v_add_f32_dpp v58, v58, v58 row_half_mirror row_mask:0xf bank_mask:0xf bound_ctrl:1
	v_add_f32_dpp v66, v66, v66 row_half_mirror row_mask:0xf bank_mask:0xf bound_ctrl:1
	v_pk_fma_f32 v[62:63], v[92:93], v[150:151], v[62:63]
	v_add_f32_dpp v58, v58, v58 row_mirror row_mask:0xf bank_mask:0xf bound_ctrl:1
	v_add_f32_dpp v66, v66, v66 row_mirror row_mask:0xf bank_mask:0xf bound_ctrl:1
	v_pk_fma_f32 v[90:91], v[156:157], v[58:59], v[60:61] op_sel_hi:[1,0,1] neg_lo:[1,0,0] neg_hi:[1,0,0]
	v_pk_fma_f32 v[92:93], v[158:159], v[58:59], v[62:63] op_sel_hi:[1,0,1] neg_lo:[1,0,0] neg_hi:[1,0,0]
	v_cndmask_b32_e64 v67, v67, v66, s[66:67]
	s_nop 0
	v_pk_mul_f32 v[64:65], v[142:143], v[92:93]
	s_cmpk_gt_u32 s26, 0xff
	s_movk_i32 s12, 0x11ff
	s_cselect_b32 s12, s12, 0xff
	v_pk_fma_f32 v[64:65], v[140:141], v[90:91], v[64:65]
	s_sub_i32 s12, s12, s26
	v_add_u32_e32 v46, s26, v36
	v_add_f32_e32 v66, v64, v65
	v_sub_u32_e32 v47, s12, v36
	v_cndmask_b32_e64 v46, v47, v46, s[36:37]
	v_add_f32_dpp v66, v66, v66 quad_perm:[1,0,3,2] row_mask:0xf bank_mask:0xf bound_ctrl:1
	v_mov_b32_e32 v47, 0
	v_lshlrev_b64 v[46:47], 9, v[46:47]
	v_add_f32_dpp v66, v66, v66 quad_perm:[2,3,0,1] row_mask:0xf bank_mask:0xf bound_ctrl:1
	v_lshl_add_u64 v[46:47], v[30:31], 0, v[46:47]
	s_nop 0
	v_add_f32_dpp v66, v66, v66 row_half_mirror row_mask:0xf bank_mask:0xf bound_ctrl:1
	s_nop 1
	v_add_f32_dpp v66, v66, v66 row_mirror row_mask:0xf bank_mask:0xf bound_ctrl:1
	v_cndmask_b32_e64 v67, v67, v66, s[68:69]
	v_cvt_f16_f32_e32 v45, v67
	global_store_short v[46:47], v45, off
	s_waitcnt vmcnt(6)
	v_cvt_f32_f16_e32 v40, v162
	v_cvt_f32_f16_sdwa v41, v162 dst_sel:DWORD dst_unused:UNUSED_PAD src0_sel:WORD_1
	v_cvt_f32_f16_e32 v42, v163
	v_cvt_f32_f16_sdwa v43, v163 dst_sel:DWORD dst_unused:UNUSED_PAD src0_sel:WORD_1
	v_cvt_f32_f16_e32 v44, v164
	v_cvt_f32_f16_sdwa v45, v164 dst_sel:DWORD dst_unused:UNUSED_PAD src0_sel:WORD_1
	v_cvt_f32_f16_e32 v46, v165
	v_cvt_f32_f16_sdwa v47, v165 dst_sel:DWORD dst_unused:UNUSED_PAD src0_sel:WORD_1
	ds_write_b128 v32, v[40:43]
	ds_write_b128 v32, v[44:47] offset:16
	s_waitcnt vmcnt(5)
	v_cvt_f32_f16_e32 v40, v166
	v_cvt_f32_f16_sdwa v41, v166 dst_sel:DWORD dst_unused:UNUSED_PAD src0_sel:WORD_1
	v_cvt_f32_f16_e32 v42, v167
	v_cvt_f32_f16_sdwa v43, v167 dst_sel:DWORD dst_unused:UNUSED_PAD src0_sel:WORD_1
	v_cvt_f32_f16_e32 v44, v168
	v_cvt_f32_f16_sdwa v45, v168 dst_sel:DWORD dst_unused:UNUSED_PAD src0_sel:WORD_1
	v_cvt_f32_f16_e32 v46, v169
	v_cvt_f32_f16_sdwa v47, v169 dst_sel:DWORD dst_unused:UNUSED_PAD src0_sel:WORD_1
	ds_write_b128 v33, v[40:43]
	ds_write_b128 v33, v[44:47] offset:16
	s_waitcnt vmcnt(4)
	v_cvt_f32_f16_e32 v40, v170
	v_cvt_f32_f16_sdwa v41, v170 dst_sel:DWORD dst_unused:UNUSED_PAD src0_sel:WORD_1
	v_cvt_f32_f16_e32 v42, v171
	v_cvt_f32_f16_sdwa v43, v171 dst_sel:DWORD dst_unused:UNUSED_PAD src0_sel:WORD_1
	v_cvt_f32_f16_e32 v44, v172
	v_cvt_f32_f16_sdwa v45, v172 dst_sel:DWORD dst_unused:UNUSED_PAD src0_sel:WORD_1
	v_cvt_f32_f16_e32 v46, v173
	v_cvt_f32_f16_sdwa v47, v173 dst_sel:DWORD dst_unused:UNUSED_PAD src0_sel:WORD_1
	ds_write_b128 v34, v[40:43]
	ds_write_b128 v34, v[44:47] offset:16
	s_add_i32 s26, s26, 16
	s_waitcnt lgkmcnt(0)
	s_barrier
	s_cmpk_lg_i32 s26, 0x1100
	s_cbranch_scc1 .Lscan_loop
	s_waitcnt vmcnt(0)
	s_branch .LBB0_155
